# pool_z phase by hand: 64-token x 256-channel tiles staged once in LDS (64+2hw rows), window sums formed from LDS in the baseline's operation order, rstd via one broadcast load + readlane
# speedup vs baseline: 1.0049x; 1.0049x over previous
.Lxbn8_end:
.LBB0_1636:
	s_or_b64 exec, exec, s[12:13]
	s_mov_b64 s[12:13], s[0:1]
	s_waitcnt lgkmcnt(0)
	v_mov_b32_e32 v0, v170
	s_barrier
	s_mov_b64 s[14:15], exec
	s_load_dwordx2 s[12:13], s[0:1], 0xe8
	v_and_b32_e32 v0, 63, v170
	v_lshlrev_b32_e32 v1, 4, v0
	v_readfirstlane_b32 s34, v170
	s_lshr_b32 s34, s34, 6
	s_waitcnt lgkmcnt(0)
	s_add_u32 s16, s12, 0x46bc000
	s_addc_u32 s17, s13, 0
	s_add_u32 s18, s12, 0x76bc000
	s_addc_u32 s19, s13, 0
	s_add_u32 s20, s12, 0x780000
	s_addc_u32 s21, s13, 0
	s_add_u32 s22, s12, 0x2ebc000
	s_addc_u32 s23, s13, 0
	s_mov_b32 s24, s2
.Lpz_tile:
	s_and_b32 s26, s24, 3
	s_lshr_b32 s28, s24, 2
	s_lshl_b32 s28, s28, 6
	s_lshl_b32 s27, 1, s26
	s_lshl_b32 s35, s27, 1
	s_add_i32 s35, s35, 64
	s_cmp_lt_u32 s28, 0x1000
	s_cbranch_scc0 .Lpz_lat
	s_and_b32 s29, s28, 0xffffff00
	s_movk_i32 s30, 0x100
	s_mov_b32 s25, 30
	s_branch .Lpz_seq
.Lpz_lat:
	s_sub_i32 s25, s28, 0x1000
	s_and_b32 s29, s25, 0xfffff800
	s_add_i32 s29, s29, 0x1000
	s_movk_i32 s30, 0x800
	s_lshr_b32 s25, s25, 11
	s_mul_i32 s25, s25, 6
	s_add_i32 s25, s25, 36
.Lpz_seq:
	s_sub_i32 s31, s28, s29
	s_lshl_b32 s36, s26, 10
	v_add_u32_e32 v3, s36, v1
	s_lshl_b32 s36, s26, 9
	v_lshlrev_b32_e32 v7, 3, v0
	v_add_u32_e32 v7, s36, v7
	s_lshl_b32 s36, s25, 12
	v_add_u32_e32 v2, s36, v3
	global_load_dwordx4 v[108:111], v2, s[20:21]
	s_add_i32 s40, s34, 0
	s_cmp_ge_u32 s40, s35
	s_cbranch_scc1 .Lpz_ld0
	s_add_i32 s41, s31, s40
	s_sub_i32 s41, s41, s27
	s_max_i32 s41, s41, 0
	s_add_i32 s45, s30, -1
	s_min_i32 s41, s41, s45
	s_add_i32 s41, s41, s29
	s_lshl_b32 s41, s41, 12
	s_add_u32 s36, s16, s41
	s_addc_u32 s37, s17, 0
	global_load_dwordx4 v[8:11], v3, s[36:37]
	s_add_i32 s40, s34, 8
	s_cmp_ge_u32 s40, s35
	s_cbranch_scc1 .Lpz_ld1
	s_add_i32 s41, s31, s40
	s_sub_i32 s41, s41, s27
	s_max_i32 s41, s41, 0
	s_add_i32 s45, s30, -1
	s_min_i32 s41, s41, s45
	s_add_i32 s41, s41, s29
	s_lshl_b32 s41, s41, 12
	s_add_u32 s36, s16, s41
	s_addc_u32 s37, s17, 0
	global_load_dwordx4 v[12:15], v3, s[36:37]
	s_add_i32 s40, s34, 16
	s_cmp_ge_u32 s40, s35
	s_cbranch_scc1 .Lpz_ld2
	s_add_i32 s41, s31, s40
	s_sub_i32 s41, s41, s27
	s_max_i32 s41, s41, 0
	s_add_i32 s45, s30, -1
	s_min_i32 s41, s41, s45
	s_add_i32 s41, s41, s29
	s_lshl_b32 s41, s41, 12
	s_add_u32 s36, s16, s41
	s_addc_u32 s37, s17, 0
	global_load_dwordx4 v[16:19], v3, s[36:37]
	s_add_i32 s40, s34, 24
	s_cmp_ge_u32 s40, s35
	s_cbranch_scc1 .Lpz_ld3
	s_add_i32 s41, s31, s40
	s_sub_i32 s41, s41, s27
	s_max_i32 s41, s41, 0
	s_add_i32 s45, s30, -1
	s_min_i32 s41, s41, s45
	s_add_i32 s41, s41, s29
	s_lshl_b32 s41, s41, 12
	s_add_u32 s36, s16, s41
	s_addc_u32 s37, s17, 0
	global_load_dwordx4 v[20:23], v3, s[36:37]
	s_add_i32 s40, s34, 32
	s_cmp_ge_u32 s40, s35
	s_cbranch_scc1 .Lpz_ld4
	s_add_i32 s41, s31, s40
	s_sub_i32 s41, s41, s27
	s_max_i32 s41, s41, 0
	s_add_i32 s45, s30, -1
	s_min_i32 s41, s41, s45
	s_add_i32 s41, s41, s29
	s_lshl_b32 s41, s41, 12
	s_add_u32 s36, s16, s41
	s_addc_u32 s37, s17, 0
	global_load_dwordx4 v[24:27], v3, s[36:37]
	s_add_i32 s40, s34, 40
	s_cmp_ge_u32 s40, s35
	s_cbranch_scc1 .Lpz_ld5
	s_add_i32 s41, s31, s40
	s_sub_i32 s41, s41, s27
	s_max_i32 s41, s41, 0
	s_add_i32 s45, s30, -1
	s_min_i32 s41, s41, s45
	s_add_i32 s41, s41, s29
	s_lshl_b32 s41, s41, 12
	s_add_u32 s36, s16, s41
	s_addc_u32 s37, s17, 0
	global_load_dwordx4 v[28:31], v3, s[36:37]
	s_add_i32 s40, s34, 48
	s_cmp_ge_u32 s40, s35
	s_cbranch_scc1 .Lpz_ld6
	s_add_i32 s41, s31, s40
	s_sub_i32 s41, s41, s27
	s_max_i32 s41, s41, 0
	s_add_i32 s45, s30, -1
	s_min_i32 s41, s41, s45
	s_add_i32 s41, s41, s29
	s_lshl_b32 s41, s41, 12
	s_add_u32 s36, s16, s41
	s_addc_u32 s37, s17, 0
	global_load_dwordx4 v[32:35], v3, s[36:37]
	s_add_i32 s40, s34, 56
	s_cmp_ge_u32 s40, s35
	s_cbranch_scc1 .Lpz_ld7
	s_add_i32 s41, s31, s40
	s_sub_i32 s41, s41, s27
	s_max_i32 s41, s41, 0
	s_add_i32 s45, s30, -1
	s_min_i32 s41, s41, s45
	s_add_i32 s41, s41, s29
	s_lshl_b32 s41, s41, 12
	s_add_u32 s36, s16, s41
	s_addc_u32 s37, s17, 0
	global_load_dwordx4 v[36:39], v3, s[36:37]
	s_add_i32 s40, s34, 64
	s_cmp_ge_u32 s40, s35
	s_cbranch_scc1 .Lpz_ld8
	s_add_i32 s41, s31, s40
	s_sub_i32 s41, s41, s27
	s_max_i32 s41, s41, 0
	s_add_i32 s45, s30, -1
	s_min_i32 s41, s41, s45
	s_add_i32 s41, s41, s29
	s_lshl_b32 s41, s41, 12
	s_add_u32 s36, s16, s41
	s_addc_u32 s37, s17, 0
	global_load_dwordx4 v[40:43], v3, s[36:37]
	s_add_i32 s40, s34, 72
	s_cmp_ge_u32 s40, s35
	s_cbranch_scc1 .Lpz_ld9
	s_add_i32 s41, s31, s40
	s_sub_i32 s41, s41, s27
	s_max_i32 s41, s41, 0
	s_add_i32 s45, s30, -1
	s_min_i32 s41, s41, s45
	s_add_i32 s41, s41, s29
	s_lshl_b32 s41, s41, 12
	s_add_u32 s36, s16, s41
	s_addc_u32 s37, s17, 0
	global_load_dwordx4 v[44:47], v3, s[36:37]
	s_mov_b32 s47, 10
	s_branch .Lpz_st
.Lpz_ld0:
	s_mov_b32 s47, 0
	s_branch .Lpz_st
.Lpz_ld1:
	s_mov_b32 s47, 1
	s_branch .Lpz_st
.Lpz_ld2:
	s_mov_b32 s47, 2
	s_branch .Lpz_st
.Lpz_ld3:
	s_mov_b32 s47, 3
	s_branch .Lpz_st
.Lpz_ld4:
	s_mov_b32 s47, 4
	s_branch .Lpz_st
.Lpz_ld5:
	s_mov_b32 s47, 5
	s_branch .Lpz_st
.Lpz_ld6:
	s_mov_b32 s47, 6
	s_branch .Lpz_st
.Lpz_ld7:
	s_mov_b32 s47, 7
	s_branch .Lpz_st
.Lpz_ld8:
	s_mov_b32 s47, 8
	s_branch .Lpz_st
.Lpz_ld9:
	s_mov_b32 s47, 9
.Lpz_st:
	s_waitcnt vmcnt(0)
	s_cmp_le_u32 s47, 0
	s_cbranch_scc1 .Lpz_filled
	s_add_i32 s40, s34, 0
	s_lshl_b32 s40, s40, 10
	v_add_u32_e32 v4, s40, v1
	ds_write_b128 v4, v[8:11]
	s_cmp_le_u32 s47, 1
	s_cbranch_scc1 .Lpz_filled
	s_add_i32 s40, s34, 8
	s_lshl_b32 s40, s40, 10
	v_add_u32_e32 v4, s40, v1
	ds_write_b128 v4, v[12:15]
	s_cmp_le_u32 s47, 2
	s_cbranch_scc1 .Lpz_filled
	s_add_i32 s40, s34, 16
	s_lshl_b32 s40, s40, 10
	v_add_u32_e32 v4, s40, v1
	ds_write_b128 v4, v[16:19]
	s_cmp_le_u32 s47, 3
	s_cbranch_scc1 .Lpz_filled
	s_add_i32 s40, s34, 24
	s_lshl_b32 s40, s40, 10
	v_add_u32_e32 v4, s40, v1
	ds_write_b128 v4, v[20:23]
	s_cmp_le_u32 s47, 4
	s_cbranch_scc1 .Lpz_filled
	s_add_i32 s40, s34, 32
	s_lshl_b32 s40, s40, 10
	v_add_u32_e32 v4, s40, v1
	ds_write_b128 v4, v[24:27]
	s_cmp_le_u32 s47, 5
	s_cbranch_scc1 .Lpz_filled
	s_add_i32 s40, s34, 40
	s_lshl_b32 s40, s40, 10
	v_add_u32_e32 v4, s40, v1
	ds_write_b128 v4, v[28:31]
	s_cmp_le_u32 s47, 6
	s_cbranch_scc1 .Lpz_filled
	s_add_i32 s40, s34, 48
	s_lshl_b32 s40, s40, 10
	v_add_u32_e32 v4, s40, v1
	ds_write_b128 v4, v[32:35]
	s_cmp_le_u32 s47, 7
	s_cbranch_scc1 .Lpz_filled
	s_add_i32 s40, s34, 56
	s_lshl_b32 s40, s40, 10
	v_add_u32_e32 v4, s40, v1
	ds_write_b128 v4, v[36:39]
	s_cmp_le_u32 s47, 8
	s_cbranch_scc1 .Lpz_filled
	s_add_i32 s40, s34, 64
	s_lshl_b32 s40, s40, 10
	v_add_u32_e32 v4, s40, v1
	ds_write_b128 v4, v[40:43]
	s_cmp_le_u32 s47, 9
	s_cbranch_scc1 .Lpz_filled
	s_add_i32 s40, s34, 72
	s_lshl_b32 s40, s40, 10
	v_add_u32_e32 v4, s40, v1
	ds_write_b128 v4, v[44:47]
.Lpz_filled:
	s_waitcnt lgkmcnt(0)
	s_barrier
	s_cmp_eq_u32 s26, 0
	s_cbranch_scc1 .Lpz_c0
	s_cmp_eq_u32 s26, 1
	s_cbranch_scc1 .Lpz_c1
	s_cmp_eq_u32 s26, 2
	s_cbranch_scc1 .Lpz_c2
.Lpz_c3:
	s_lshl_b32 s40, s34, 3
	s_lshl_b32 s41, s40, 10
	v_add_u32_e32 v4, s41, v1
	ds_read_b128 v[8:11], v4
	ds_read_b128 v[12:15], v4 offset:1024
	ds_read_b128 v[16:19], v4 offset:2048
	ds_read_b128 v[20:23], v4 offset:3072
	ds_read_b128 v[24:27], v4 offset:4096
	ds_read_b128 v[28:31], v4 offset:5120
	ds_read_b128 v[32:35], v4 offset:6144
	ds_read_b128 v[36:39], v4 offset:7168
	ds_read_b128 v[40:43], v4 offset:8192
	ds_read_b128 v[44:47], v4 offset:9216
	ds_read_b128 v[48:51], v4 offset:10240
	ds_read_b128 v[52:55], v4 offset:11264
	ds_read_b128 v[56:59], v4 offset:12288
	ds_read_b128 v[60:63], v4 offset:13312
	ds_read_b128 v[64:67], v4 offset:14336
	ds_read_b128 v[68:71], v4 offset:15360
	ds_read_b128 v[72:75], v4 offset:16384
	ds_read_b128 v[76:79], v4 offset:17408
	ds_read_b128 v[80:83], v4 offset:18432
	s_add_i32 s41, s31, s40
	s_sub_i32 s41, s41, 8
	v_add_u32_e32 v5, s41, v0
	v_cmp_le_i32_e64 s[36:37], 0, v5
	v_cmp_gt_i32_e64 s[12:13], s30, v5
	s_and_b64 s[36:37], s[36:37], s[12:13]
	v_max_i32_e32 v5, 0, v5
	s_add_i32 s41, s30, -1
	v_min_i32_e32 v5, s41, v5
	v_add_u32_e32 v5, s29, v5
	v_lshlrev_b32_e32 v5, 2, v5
	global_load_dword v6, v5, s[18:19]
	s_waitcnt vmcnt(0)
	v_cndmask_b32_e64 v6, 0, v6, s[36:37]
	s_add_i32 s45, s31, s40
	s_waitcnt lgkmcnt(0)
	v_readlane_b32 s36, v6, 0
	v_pk_fma_f32 v[104:105], s[36:37], v[8:9], 0 op_sel_hi:[0,1,0]
	v_pk_fma_f32 v[106:107], s[36:37], v[10:11], 0 op_sel_hi:[0,1,0]
	v_readlane_b32 s12, v6, 1
	v_pk_fma_f32 v[104:105], s[12:13], v[12:13], v[104:105] op_sel_hi:[0,1,1]
	v_pk_fma_f32 v[106:107], s[12:13], v[14:15], v[106:107] op_sel_hi:[0,1,1]
	v_readlane_b32 s36, v6, 2
	v_pk_fma_f32 v[104:105], s[36:37], v[16:17], v[104:105] op_sel_hi:[0,1,1]
	v_pk_fma_f32 v[106:107], s[36:37], v[18:19], v[106:107] op_sel_hi:[0,1,1]
	v_readlane_b32 s12, v6, 3
	v_pk_fma_f32 v[104:105], s[12:13], v[20:21], v[104:105] op_sel_hi:[0,1,1]
	v_pk_fma_f32 v[106:107], s[12:13], v[22:23], v[106:107] op_sel_hi:[0,1,1]
	v_readlane_b32 s36, v6, 4
	v_pk_fma_f32 v[104:105], s[36:37], v[24:25], v[104:105] op_sel_hi:[0,1,1]
	v_pk_fma_f32 v[106:107], s[36:37], v[26:27], v[106:107] op_sel_hi:[0,1,1]
	v_readlane_b32 s12, v6, 5
	v_pk_fma_f32 v[104:105], s[12:13], v[28:29], v[104:105] op_sel_hi:[0,1,1]
	v_pk_fma_f32 v[106:107], s[12:13], v[30:31], v[106:107] op_sel_hi:[0,1,1]
	v_readlane_b32 s36, v6, 6
	v_pk_fma_f32 v[104:105], s[36:37], v[32:33], v[104:105] op_sel_hi:[0,1,1]
	v_pk_fma_f32 v[106:107], s[36:37], v[34:35], v[106:107] op_sel_hi:[0,1,1]
	v_readlane_b32 s12, v6, 7
	v_pk_fma_f32 v[104:105], s[12:13], v[36:37], v[104:105] op_sel_hi:[0,1,1]
	v_pk_fma_f32 v[106:107], s[12:13], v[38:39], v[106:107] op_sel_hi:[0,1,1]
	v_readlane_b32 s36, v6, 8
	v_pk_fma_f32 v[104:105], s[36:37], v[40:41], v[104:105] op_sel_hi:[0,1,1]
	v_pk_fma_f32 v[106:107], s[36:37], v[42:43], v[106:107] op_sel_hi:[0,1,1]
	v_readlane_b32 s12, v6, 9
	v_pk_fma_f32 v[104:105], s[12:13], v[44:45], v[104:105] op_sel_hi:[0,1,1]
	v_pk_fma_f32 v[106:107], s[12:13], v[46:47], v[106:107] op_sel_hi:[0,1,1]
	v_readlane_b32 s36, v6, 10
	v_pk_fma_f32 v[104:105], s[36:37], v[48:49], v[104:105] op_sel_hi:[0,1,1]
	v_pk_fma_f32 v[106:107], s[36:37], v[50:51], v[106:107] op_sel_hi:[0,1,1]
	v_readlane_b32 s12, v6, 11
	v_pk_fma_f32 v[104:105], s[12:13], v[52:53], v[104:105] op_sel_hi:[0,1,1]
	v_pk_fma_f32 v[106:107], s[12:13], v[54:55], v[106:107] op_sel_hi:[0,1,1]
	v_readlane_b32 s36, v6, 12
	v_pk_fma_f32 v[104:105], s[36:37], v[56:57], v[104:105] op_sel_hi:[0,1,1]
	v_pk_fma_f32 v[106:107], s[36:37], v[58:59], v[106:107] op_sel_hi:[0,1,1]
	v_readlane_b32 s12, v6, 13
	v_pk_fma_f32 v[104:105], s[12:13], v[60:61], v[104:105] op_sel_hi:[0,1,1]
	v_pk_fma_f32 v[106:107], s[12:13], v[62:63], v[106:107] op_sel_hi:[0,1,1]
	v_readlane_b32 s36, v6, 14
	v_pk_fma_f32 v[104:105], s[36:37], v[64:65], v[104:105] op_sel_hi:[0,1,1]
	v_pk_fma_f32 v[106:107], s[36:37], v[66:67], v[106:107] op_sel_hi:[0,1,1]
	v_readlane_b32 s12, v6, 15
	v_pk_fma_f32 v[104:105], s[12:13], v[68:69], v[104:105] op_sel_hi:[0,1,1]
	v_pk_fma_f32 v[106:107], s[12:13], v[70:71], v[106:107] op_sel_hi:[0,1,1]
	s_add_i32 s47, s45, 8
	s_min_u32 s47, s47, s30
	s_add_i32 s50, s45, -8
	s_max_i32 s50, s50, 0
	s_sub_i32 s47, s47, s50
	v_cvt_f32_i32_e32 v116, s47
	v_div_scale_f32 v120, s[12:13], v116, v116, 1.0
	v_rcp_f32_e32 v121, v120
	v_div_scale_f32 v122, vcc, 1.0, v116, 1.0
	s_nop 0
	v_fma_f32 v124, -v120, v121, 1.0
	v_fmac_f32_e32 v121, v124, v121
	v_mul_f32_e32 v123, v122, v121
	v_fma_f32 v124, -v120, v123, v122
	v_fmac_f32_e32 v123, v124, v121
	v_fma_f32 v120, -v120, v123, v122
	v_div_fmas_f32 v120, v120, v121, v123
	v_div_fixup_f32 v118, v120, v116, 1.0
	v_readlane_b32 s36, v6, 8
	v_pk_mul_f32 v[112:113], s[36:37], v[40:41] op_sel_hi:[0,1]
	v_pk_mul_f32 v[114:115], s[36:37], v[42:43] op_sel_hi:[0,1]
	v_pk_fma_f32 v[112:113], v[118:119], v[104:105], v[112:113] op_sel_hi:[0,1,1] neg_lo:[0,0,1] neg_hi:[0,0,1]
	v_pk_fma_f32 v[114:115], v[118:119], v[106:107], v[114:115] op_sel_hi:[0,1,1] neg_lo:[0,0,1] neg_hi:[0,0,1]
	v_pk_mul_f32 v[112:113], v[108:109], v[112:113]
	v_pk_mul_f32 v[114:115], v[110:111], v[114:115]
	v_cvt_pk_bf16_f32 v128, v112, v113
	v_cvt_pk_bf16_f32 v129, v114, v115
	s_add_i32 s47, s28, s40
	s_add_i32 s47, s47, 0
	s_lshl_b32 s47, s47, 11
	v_add_u32_e32 v130, s47, v7
	global_store_dwordx2 v130, v[128:129], s[22:23]
	v_readlane_b32 s36, v6, 0
	v_readlane_b32 s12, v6, 16
	v_pk_mul_f32 v[112:113], s[36:37], v[8:9] op_sel_hi:[0,1]
	v_pk_mul_f32 v[114:115], s[36:37], v[10:11] op_sel_hi:[0,1]
	v_pk_fma_f32 v[112:113], s[12:13], v[72:73], v[112:113] op_sel_hi:[0,1,1] neg_lo:[0,0,1] neg_hi:[0,0,1]
	v_pk_fma_f32 v[114:115], s[12:13], v[74:75], v[114:115] op_sel_hi:[0,1,1] neg_lo:[0,0,1] neg_hi:[0,0,1]
	v_pk_add_f32 v[104:105], v[104:105], v[112:113]
	v_pk_add_f32 v[106:107], v[106:107], v[114:115]
	s_add_i32 s47, s45, 9
	s_min_u32 s47, s47, s30
	s_add_i32 s50, s45, -7
	s_max_i32 s50, s50, 0
	s_sub_i32 s47, s47, s50
	v_cvt_f32_i32_e32 v116, s47
	v_div_scale_f32 v120, s[12:13], v116, v116, 1.0
	v_rcp_f32_e32 v121, v120
	v_div_scale_f32 v122, vcc, 1.0, v116, 1.0
	s_nop 0
	v_fma_f32 v124, -v120, v121, 1.0
	v_fmac_f32_e32 v121, v124, v121
	v_mul_f32_e32 v123, v122, v121
	v_fma_f32 v124, -v120, v123, v122
	v_fmac_f32_e32 v123, v124, v121
	v_fma_f32 v120, -v120, v123, v122
	v_div_fmas_f32 v120, v120, v121, v123
	v_div_fixup_f32 v118, v120, v116, 1.0
	v_readlane_b32 s36, v6, 9
	v_pk_mul_f32 v[112:113], s[36:37], v[44:45] op_sel_hi:[0,1]
	v_pk_mul_f32 v[114:115], s[36:37], v[46:47] op_sel_hi:[0,1]
	v_pk_fma_f32 v[112:113], v[118:119], v[104:105], v[112:113] op_sel_hi:[0,1,1] neg_lo:[0,0,1] neg_hi:[0,0,1]
	v_pk_fma_f32 v[114:115], v[118:119], v[106:107], v[114:115] op_sel_hi:[0,1,1] neg_lo:[0,0,1] neg_hi:[0,0,1]
	v_pk_mul_f32 v[112:113], v[108:109], v[112:113]
	v_pk_mul_f32 v[114:115], v[110:111], v[114:115]
	v_cvt_pk_bf16_f32 v128, v112, v113
	v_cvt_pk_bf16_f32 v129, v114, v115
	s_add_i32 s47, s28, s40
	s_add_i32 s47, s47, 1
	s_lshl_b32 s47, s47, 11
	v_add_u32_e32 v130, s47, v7
	global_store_dwordx2 v130, v[128:129], s[22:23]
	v_readlane_b32 s36, v6, 1
	v_readlane_b32 s12, v6, 17
	v_pk_mul_f32 v[112:113], s[36:37], v[12:13] op_sel_hi:[0,1]
	v_pk_mul_f32 v[114:115], s[36:37], v[14:15] op_sel_hi:[0,1]
	v_pk_fma_f32 v[112:113], s[12:13], v[76:77], v[112:113] op_sel_hi:[0,1,1] neg_lo:[0,0,1] neg_hi:[0,0,1]
	v_pk_fma_f32 v[114:115], s[12:13], v[78:79], v[114:115] op_sel_hi:[0,1,1] neg_lo:[0,0,1] neg_hi:[0,0,1]
	v_pk_add_f32 v[104:105], v[104:105], v[112:113]
	v_pk_add_f32 v[106:107], v[106:107], v[114:115]
	s_add_i32 s47, s45, 10
	s_min_u32 s47, s47, s30
	s_add_i32 s50, s45, -6
	s_max_i32 s50, s50, 0
	s_sub_i32 s47, s47, s50
	v_cvt_f32_i32_e32 v116, s47
	v_div_scale_f32 v120, s[12:13], v116, v116, 1.0
	v_rcp_f32_e32 v121, v120
	v_div_scale_f32 v122, vcc, 1.0, v116, 1.0
	s_nop 0
	v_fma_f32 v124, -v120, v121, 1.0
	v_fmac_f32_e32 v121, v124, v121
	v_mul_f32_e32 v123, v122, v121
	v_fma_f32 v124, -v120, v123, v122
	v_fmac_f32_e32 v123, v124, v121
	v_fma_f32 v120, -v120, v123, v122
	v_div_fmas_f32 v120, v120, v121, v123
	v_div_fixup_f32 v118, v120, v116, 1.0
	v_readlane_b32 s36, v6, 10
	v_pk_mul_f32 v[112:113], s[36:37], v[48:49] op_sel_hi:[0,1]
	v_pk_mul_f32 v[114:115], s[36:37], v[50:51] op_sel_hi:[0,1]
	v_pk_fma_f32 v[112:113], v[118:119], v[104:105], v[112:113] op_sel_hi:[0,1,1] neg_lo:[0,0,1] neg_hi:[0,0,1]
	v_pk_fma_f32 v[114:115], v[118:119], v[106:107], v[114:115] op_sel_hi:[0,1,1] neg_lo:[0,0,1] neg_hi:[0,0,1]
	v_pk_mul_f32 v[112:113], v[108:109], v[112:113]
	v_pk_mul_f32 v[114:115], v[110:111], v[114:115]
	v_cvt_pk_bf16_f32 v128, v112, v113
	v_cvt_pk_bf16_f32 v129, v114, v115
	s_add_i32 s47, s28, s40
	s_add_i32 s47, s47, 2
	s_lshl_b32 s47, s47, 11
	v_add_u32_e32 v130, s47, v7
	global_store_dwordx2 v130, v[128:129], s[22:23]
	v_readlane_b32 s36, v6, 2
	v_readlane_b32 s12, v6, 18
	v_pk_mul_f32 v[112:113], s[36:37], v[16:17] op_sel_hi:[0,1]
	v_pk_mul_f32 v[114:115], s[36:37], v[18:19] op_sel_hi:[0,1]
	v_pk_fma_f32 v[112:113], s[12:13], v[80:81], v[112:113] op_sel_hi:[0,1,1] neg_lo:[0,0,1] neg_hi:[0,0,1]
	v_pk_fma_f32 v[114:115], s[12:13], v[82:83], v[114:115] op_sel_hi:[0,1,1] neg_lo:[0,0,1] neg_hi:[0,0,1]
	v_pk_add_f32 v[104:105], v[104:105], v[112:113]
	v_pk_add_f32 v[106:107], v[106:107], v[114:115]
	s_add_i32 s47, s45, 11
	s_min_u32 s47, s47, s30
	s_add_i32 s50, s45, -5
	s_max_i32 s50, s50, 0
	s_sub_i32 s47, s47, s50
	v_cvt_f32_i32_e32 v116, s47
	v_div_scale_f32 v120, s[12:13], v116, v116, 1.0
	v_rcp_f32_e32 v121, v120
	v_div_scale_f32 v122, vcc, 1.0, v116, 1.0
	s_nop 0
	v_fma_f32 v124, -v120, v121, 1.0
	v_fmac_f32_e32 v121, v124, v121
	v_mul_f32_e32 v123, v122, v121
	v_fma_f32 v124, -v120, v123, v122
	v_fmac_f32_e32 v123, v124, v121
	v_fma_f32 v120, -v120, v123, v122
	v_div_fmas_f32 v120, v120, v121, v123
	v_div_fixup_f32 v118, v120, v116, 1.0
	v_readlane_b32 s36, v6, 11
	v_pk_mul_f32 v[112:113], s[36:37], v[52:53] op_sel_hi:[0,1]
	v_pk_mul_f32 v[114:115], s[36:37], v[54:55] op_sel_hi:[0,1]
	v_pk_fma_f32 v[112:113], v[118:119], v[104:105], v[112:113] op_sel_hi:[0,1,1] neg_lo:[0,0,1] neg_hi:[0,0,1]
	v_pk_fma_f32 v[114:115], v[118:119], v[106:107], v[114:115] op_sel_hi:[0,1,1] neg_lo:[0,0,1] neg_hi:[0,0,1]
	v_pk_mul_f32 v[112:113], v[108:109], v[112:113]
	v_pk_mul_f32 v[114:115], v[110:111], v[114:115]
	v_cvt_pk_bf16_f32 v128, v112, v113
	v_cvt_pk_bf16_f32 v129, v114, v115
	s_add_i32 s47, s28, s40
	s_add_i32 s47, s47, 3
	s_lshl_b32 s47, s47, 11
	v_add_u32_e32 v130, s47, v7
	global_store_dwordx2 v130, v[128:129], s[22:23]
	s_lshl_b32 s40, s34, 3
	s_add_i32 s40, s40, 4
	s_lshl_b32 s41, s40, 10
	v_add_u32_e32 v4, s41, v1
	ds_read_b128 v[8:11], v4
	ds_read_b128 v[12:15], v4 offset:1024
	ds_read_b128 v[16:19], v4 offset:2048
	ds_read_b128 v[20:23], v4 offset:3072
	ds_read_b128 v[24:27], v4 offset:4096
	ds_read_b128 v[28:31], v4 offset:5120
	ds_read_b128 v[32:35], v4 offset:6144
	ds_read_b128 v[36:39], v4 offset:7168
	ds_read_b128 v[40:43], v4 offset:8192
	ds_read_b128 v[44:47], v4 offset:9216
	ds_read_b128 v[48:51], v4 offset:10240
	ds_read_b128 v[52:55], v4 offset:11264
	ds_read_b128 v[56:59], v4 offset:12288
	ds_read_b128 v[60:63], v4 offset:13312
	ds_read_b128 v[64:67], v4 offset:14336
	ds_read_b128 v[68:71], v4 offset:15360
	ds_read_b128 v[72:75], v4 offset:16384
	ds_read_b128 v[76:79], v4 offset:17408
	ds_read_b128 v[80:83], v4 offset:18432
	s_add_i32 s41, s31, s40
	s_sub_i32 s41, s41, 8
	v_add_u32_e32 v5, s41, v0
	v_cmp_le_i32_e64 s[36:37], 0, v5
	v_cmp_gt_i32_e64 s[12:13], s30, v5
	s_and_b64 s[36:37], s[36:37], s[12:13]
	v_max_i32_e32 v5, 0, v5
	s_add_i32 s41, s30, -1
	v_min_i32_e32 v5, s41, v5
	v_add_u32_e32 v5, s29, v5
	v_lshlrev_b32_e32 v5, 2, v5
	global_load_dword v6, v5, s[18:19]
	s_waitcnt vmcnt(0)
	v_cndmask_b32_e64 v6, 0, v6, s[36:37]
	s_add_i32 s45, s31, s40
	s_waitcnt lgkmcnt(0)
	v_readlane_b32 s36, v6, 0
	v_pk_fma_f32 v[104:105], s[36:37], v[8:9], 0 op_sel_hi:[0,1,0]
	v_pk_fma_f32 v[106:107], s[36:37], v[10:11], 0 op_sel_hi:[0,1,0]
	v_readlane_b32 s12, v6, 1
	v_pk_fma_f32 v[104:105], s[12:13], v[12:13], v[104:105] op_sel_hi:[0,1,1]
	v_pk_fma_f32 v[106:107], s[12:13], v[14:15], v[106:107] op_sel_hi:[0,1,1]
	v_readlane_b32 s36, v6, 2
	v_pk_fma_f32 v[104:105], s[36:37], v[16:17], v[104:105] op_sel_hi:[0,1,1]
	v_pk_fma_f32 v[106:107], s[36:37], v[18:19], v[106:107] op_sel_hi:[0,1,1]
	v_readlane_b32 s12, v6, 3
	v_pk_fma_f32 v[104:105], s[12:13], v[20:21], v[104:105] op_sel_hi:[0,1,1]
	v_pk_fma_f32 v[106:107], s[12:13], v[22:23], v[106:107] op_sel_hi:[0,1,1]
	v_readlane_b32 s36, v6, 4
	v_pk_fma_f32 v[104:105], s[36:37], v[24:25], v[104:105] op_sel_hi:[0,1,1]
	v_pk_fma_f32 v[106:107], s[36:37], v[26:27], v[106:107] op_sel_hi:[0,1,1]
	v_readlane_b32 s12, v6, 5
	v_pk_fma_f32 v[104:105], s[12:13], v[28:29], v[104:105] op_sel_hi:[0,1,1]
	v_pk_fma_f32 v[106:107], s[12:13], v[30:31], v[106:107] op_sel_hi:[0,1,1]
	v_readlane_b32 s36, v6, 6
	v_pk_fma_f32 v[104:105], s[36:37], v[32:33], v[104:105] op_sel_hi:[0,1,1]
	v_pk_fma_f32 v[106:107], s[36:37], v[34:35], v[106:107] op_sel_hi:[0,1,1]
	v_readlane_b32 s12, v6, 7
	v_pk_fma_f32 v[104:105], s[12:13], v[36:37], v[104:105] op_sel_hi:[0,1,1]
	v_pk_fma_f32 v[106:107], s[12:13], v[38:39], v[106:107] op_sel_hi:[0,1,1]
	v_readlane_b32 s36, v6, 8
	v_pk_fma_f32 v[104:105], s[36:37], v[40:41], v[104:105] op_sel_hi:[0,1,1]
	v_pk_fma_f32 v[106:107], s[36:37], v[42:43], v[106:107] op_sel_hi:[0,1,1]
	v_readlane_b32 s12, v6, 9
	v_pk_fma_f32 v[104:105], s[12:13], v[44:45], v[104:105] op_sel_hi:[0,1,1]
	v_pk_fma_f32 v[106:107], s[12:13], v[46:47], v[106:107] op_sel_hi:[0,1,1]
	v_readlane_b32 s36, v6, 10
	v_pk_fma_f32 v[104:105], s[36:37], v[48:49], v[104:105] op_sel_hi:[0,1,1]
	v_pk_fma_f32 v[106:107], s[36:37], v[50:51], v[106:107] op_sel_hi:[0,1,1]
	v_readlane_b32 s12, v6, 11
	v_pk_fma_f32 v[104:105], s[12:13], v[52:53], v[104:105] op_sel_hi:[0,1,1]
	v_pk_fma_f32 v[106:107], s[12:13], v[54:55], v[106:107] op_sel_hi:[0,1,1]
	v_readlane_b32 s36, v6, 12
	v_pk_fma_f32 v[104:105], s[36:37], v[56:57], v[104:105] op_sel_hi:[0,1,1]
	v_pk_fma_f32 v[106:107], s[36:37], v[58:59], v[106:107] op_sel_hi:[0,1,1]
	v_readlane_b32 s12, v6, 13
	v_pk_fma_f32 v[104:105], s[12:13], v[60:61], v[104:105] op_sel_hi:[0,1,1]
	v_pk_fma_f32 v[106:107], s[12:13], v[62:63], v[106:107] op_sel_hi:[0,1,1]
	v_readlane_b32 s36, v6, 14
	v_pk_fma_f32 v[104:105], s[36:37], v[64:65], v[104:105] op_sel_hi:[0,1,1]
	v_pk_fma_f32 v[106:107], s[36:37], v[66:67], v[106:107] op_sel_hi:[0,1,1]
	v_readlane_b32 s12, v6, 15
	v_pk_fma_f32 v[104:105], s[12:13], v[68:69], v[104:105] op_sel_hi:[0,1,1]
	v_pk_fma_f32 v[106:107], s[12:13], v[70:71], v[106:107] op_sel_hi:[0,1,1]
	s_add_i32 s47, s45, 8
	s_min_u32 s47, s47, s30
	s_add_i32 s50, s45, -8
	s_max_i32 s50, s50, 0
	s_sub_i32 s47, s47, s50
	v_cvt_f32_i32_e32 v116, s47
	v_div_scale_f32 v120, s[12:13], v116, v116, 1.0
	v_rcp_f32_e32 v121, v120
	v_div_scale_f32 v122, vcc, 1.0, v116, 1.0
	s_nop 0
	v_fma_f32 v124, -v120, v121, 1.0
	v_fmac_f32_e32 v121, v124, v121
	v_mul_f32_e32 v123, v122, v121
	v_fma_f32 v124, -v120, v123, v122
	v_fmac_f32_e32 v123, v124, v121
	v_fma_f32 v120, -v120, v123, v122
	v_div_fmas_f32 v120, v120, v121, v123
	v_div_fixup_f32 v118, v120, v116, 1.0
	v_readlane_b32 s36, v6, 8
	v_pk_mul_f32 v[112:113], s[36:37], v[40:41] op_sel_hi:[0,1]
	v_pk_mul_f32 v[114:115], s[36:37], v[42:43] op_sel_hi:[0,1]
	v_pk_fma_f32 v[112:113], v[118:119], v[104:105], v[112:113] op_sel_hi:[0,1,1] neg_lo:[0,0,1] neg_hi:[0,0,1]
	v_pk_fma_f32 v[114:115], v[118:119], v[106:107], v[114:115] op_sel_hi:[0,1,1] neg_lo:[0,0,1] neg_hi:[0,0,1]
	v_pk_mul_f32 v[112:113], v[108:109], v[112:113]
	v_pk_mul_f32 v[114:115], v[110:111], v[114:115]
	v_cvt_pk_bf16_f32 v128, v112, v113
	v_cvt_pk_bf16_f32 v129, v114, v115
	s_add_i32 s47, s28, s40
	s_add_i32 s47, s47, 0
	s_lshl_b32 s47, s47, 11
	v_add_u32_e32 v130, s47, v7
	global_store_dwordx2 v130, v[128:129], s[22:23]
	v_readlane_b32 s36, v6, 0
	v_readlane_b32 s12, v6, 16
	v_pk_mul_f32 v[112:113], s[36:37], v[8:9] op_sel_hi:[0,1]
	v_pk_mul_f32 v[114:115], s[36:37], v[10:11] op_sel_hi:[0,1]
	v_pk_fma_f32 v[112:113], s[12:13], v[72:73], v[112:113] op_sel_hi:[0,1,1] neg_lo:[0,0,1] neg_hi:[0,0,1]
	v_pk_fma_f32 v[114:115], s[12:13], v[74:75], v[114:115] op_sel_hi:[0,1,1] neg_lo:[0,0,1] neg_hi:[0,0,1]
	v_pk_add_f32 v[104:105], v[104:105], v[112:113]
	v_pk_add_f32 v[106:107], v[106:107], v[114:115]
	s_add_i32 s47, s45, 9
	s_min_u32 s47, s47, s30
	s_add_i32 s50, s45, -7
	s_max_i32 s50, s50, 0
	s_sub_i32 s47, s47, s50
	v_cvt_f32_i32_e32 v116, s47
	v_div_scale_f32 v120, s[12:13], v116, v116, 1.0
	v_rcp_f32_e32 v121, v120
	v_div_scale_f32 v122, vcc, 1.0, v116, 1.0
	s_nop 0
	v_fma_f32 v124, -v120, v121, 1.0
	v_fmac_f32_e32 v121, v124, v121
	v_mul_f32_e32 v123, v122, v121
	v_fma_f32 v124, -v120, v123, v122
	v_fmac_f32_e32 v123, v124, v121
	v_fma_f32 v120, -v120, v123, v122
	v_div_fmas_f32 v120, v120, v121, v123
	v_div_fixup_f32 v118, v120, v116, 1.0
	v_readlane_b32 s36, v6, 9
	v_pk_mul_f32 v[112:113], s[36:37], v[44:45] op_sel_hi:[0,1]
	v_pk_mul_f32 v[114:115], s[36:37], v[46:47] op_sel_hi:[0,1]
	v_pk_fma_f32 v[112:113], v[118:119], v[104:105], v[112:113] op_sel_hi:[0,1,1] neg_lo:[0,0,1] neg_hi:[0,0,1]
	v_pk_fma_f32 v[114:115], v[118:119], v[106:107], v[114:115] op_sel_hi:[0,1,1] neg_lo:[0,0,1] neg_hi:[0,0,1]
	v_pk_mul_f32 v[112:113], v[108:109], v[112:113]
	v_pk_mul_f32 v[114:115], v[110:111], v[114:115]
	v_cvt_pk_bf16_f32 v128, v112, v113
	v_cvt_pk_bf16_f32 v129, v114, v115
	s_add_i32 s47, s28, s40
	s_add_i32 s47, s47, 1
	s_lshl_b32 s47, s47, 11
	v_add_u32_e32 v130, s47, v7
	global_store_dwordx2 v130, v[128:129], s[22:23]
	v_readlane_b32 s36, v6, 1
	v_readlane_b32 s12, v6, 17
	v_pk_mul_f32 v[112:113], s[36:37], v[12:13] op_sel_hi:[0,1]
	v_pk_mul_f32 v[114:115], s[36:37], v[14:15] op_sel_hi:[0,1]
	v_pk_fma_f32 v[112:113], s[12:13], v[76:77], v[112:113] op_sel_hi:[0,1,1] neg_lo:[0,0,1] neg_hi:[0,0,1]
	v_pk_fma_f32 v[114:115], s[12:13], v[78:79], v[114:115] op_sel_hi:[0,1,1] neg_lo:[0,0,1] neg_hi:[0,0,1]
	v_pk_add_f32 v[104:105], v[104:105], v[112:113]
	v_pk_add_f32 v[106:107], v[106:107], v[114:115]
	s_add_i32 s47, s45, 10
	s_min_u32 s47, s47, s30
	s_add_i32 s50, s45, -6
	s_max_i32 s50, s50, 0
	s_sub_i32 s47, s47, s50
	v_cvt_f32_i32_e32 v116, s47
	v_div_scale_f32 v120, s[12:13], v116, v116, 1.0
	v_rcp_f32_e32 v121, v120
	v_div_scale_f32 v122, vcc, 1.0, v116, 1.0
	s_nop 0
	v_fma_f32 v124, -v120, v121, 1.0
	v_fmac_f32_e32 v121, v124, v121
	v_mul_f32_e32 v123, v122, v121
	v_fma_f32 v124, -v120, v123, v122
	v_fmac_f32_e32 v123, v124, v121
	v_fma_f32 v120, -v120, v123, v122
	v_div_fmas_f32 v120, v120, v121, v123
	v_div_fixup_f32 v118, v120, v116, 1.0
	v_readlane_b32 s36, v6, 10
	v_pk_mul_f32 v[112:113], s[36:37], v[48:49] op_sel_hi:[0,1]
	v_pk_mul_f32 v[114:115], s[36:37], v[50:51] op_sel_hi:[0,1]
	v_pk_fma_f32 v[112:113], v[118:119], v[104:105], v[112:113] op_sel_hi:[0,1,1] neg_lo:[0,0,1] neg_hi:[0,0,1]
	v_pk_fma_f32 v[114:115], v[118:119], v[106:107], v[114:115] op_sel_hi:[0,1,1] neg_lo:[0,0,1] neg_hi:[0,0,1]
	v_pk_mul_f32 v[112:113], v[108:109], v[112:113]
	v_pk_mul_f32 v[114:115], v[110:111], v[114:115]
	v_cvt_pk_bf16_f32 v128, v112, v113
	v_cvt_pk_bf16_f32 v129, v114, v115
	s_add_i32 s47, s28, s40
	s_add_i32 s47, s47, 2
	s_lshl_b32 s47, s47, 11
	v_add_u32_e32 v130, s47, v7
	global_store_dwordx2 v130, v[128:129], s[22:23]
	v_readlane_b32 s36, v6, 2
	v_readlane_b32 s12, v6, 18
	v_pk_mul_f32 v[112:113], s[36:37], v[16:17] op_sel_hi:[0,1]
	v_pk_mul_f32 v[114:115], s[36:37], v[18:19] op_sel_hi:[0,1]
	v_pk_fma_f32 v[112:113], s[12:13], v[80:81], v[112:113] op_sel_hi:[0,1,1] neg_lo:[0,0,1] neg_hi:[0,0,1]
	v_pk_fma_f32 v[114:115], s[12:13], v[82:83], v[114:115] op_sel_hi:[0,1,1] neg_lo:[0,0,1] neg_hi:[0,0,1]
	v_pk_add_f32 v[104:105], v[104:105], v[112:113]
	v_pk_add_f32 v[106:107], v[106:107], v[114:115]
	s_add_i32 s47, s45, 11
	s_min_u32 s47, s47, s30
	s_add_i32 s50, s45, -5
	s_max_i32 s50, s50, 0
	s_sub_i32 s47, s47, s50
	v_cvt_f32_i32_e32 v116, s47
	v_div_scale_f32 v120, s[12:13], v116, v116, 1.0
	v_rcp_f32_e32 v121, v120
	v_div_scale_f32 v122, vcc, 1.0, v116, 1.0
	s_nop 0
	v_fma_f32 v124, -v120, v121, 1.0
	v_fmac_f32_e32 v121, v124, v121
	v_mul_f32_e32 v123, v122, v121
	v_fma_f32 v124, -v120, v123, v122
	v_fmac_f32_e32 v123, v124, v121
	v_fma_f32 v120, -v120, v123, v122
	v_div_fmas_f32 v120, v120, v121, v123
	v_div_fixup_f32 v118, v120, v116, 1.0
	v_readlane_b32 s36, v6, 11
	v_pk_mul_f32 v[112:113], s[36:37], v[52:53] op_sel_hi:[0,1]
	v_pk_mul_f32 v[114:115], s[36:37], v[54:55] op_sel_hi:[0,1]
	v_pk_fma_f32 v[112:113], v[118:119], v[104:105], v[112:113] op_sel_hi:[0,1,1] neg_lo:[0,0,1] neg_hi:[0,0,1]
	v_pk_fma_f32 v[114:115], v[118:119], v[106:107], v[114:115] op_sel_hi:[0,1,1] neg_lo:[0,0,1] neg_hi:[0,0,1]
	v_pk_mul_f32 v[112:113], v[108:109], v[112:113]
	v_pk_mul_f32 v[114:115], v[110:111], v[114:115]
	v_cvt_pk_bf16_f32 v128, v112, v113
	v_cvt_pk_bf16_f32 v129, v114, v115
	s_add_i32 s47, s28, s40
	s_add_i32 s47, s47, 3
	s_lshl_b32 s47, s47, 11
	v_add_u32_e32 v130, s47, v7
	global_store_dwordx2 v130, v[128:129], s[22:23]
	s_branch .Lpz_next
.Lpz_c2:
	s_lshl_b32 s40, s34, 3
	s_lshl_b32 s41, s40, 10
	v_add_u32_e32 v4, s41, v1
	ds_read_b128 v[8:11], v4
	ds_read_b128 v[12:15], v4 offset:1024
	ds_read_b128 v[16:19], v4 offset:2048
	ds_read_b128 v[20:23], v4 offset:3072
	ds_read_b128 v[24:27], v4 offset:4096
	ds_read_b128 v[28:31], v4 offset:5120
	ds_read_b128 v[32:35], v4 offset:6144
	ds_read_b128 v[36:39], v4 offset:7168
	ds_read_b128 v[40:43], v4 offset:8192
	ds_read_b128 v[44:47], v4 offset:9216
	ds_read_b128 v[48:51], v4 offset:10240
	s_add_i32 s41, s31, s40
	s_sub_i32 s41, s41, 4
	v_add_u32_e32 v5, s41, v0
	v_cmp_le_i32_e64 s[36:37], 0, v5
	v_cmp_gt_i32_e64 s[12:13], s30, v5
	s_and_b64 s[36:37], s[36:37], s[12:13]
	v_max_i32_e32 v5, 0, v5
	s_add_i32 s41, s30, -1
	v_min_i32_e32 v5, s41, v5
	v_add_u32_e32 v5, s29, v5
	v_lshlrev_b32_e32 v5, 2, v5
	global_load_dword v6, v5, s[18:19]
	s_waitcnt vmcnt(0)
	v_cndmask_b32_e64 v6, 0, v6, s[36:37]
	s_add_i32 s45, s31, s40
	s_waitcnt lgkmcnt(0)
	v_readlane_b32 s36, v6, 0
	v_pk_fma_f32 v[104:105], s[36:37], v[8:9], 0 op_sel_hi:[0,1,0]
	v_pk_fma_f32 v[106:107], s[36:37], v[10:11], 0 op_sel_hi:[0,1,0]
	v_readlane_b32 s12, v6, 1
	v_pk_fma_f32 v[104:105], s[12:13], v[12:13], v[104:105] op_sel_hi:[0,1,1]
	v_pk_fma_f32 v[106:107], s[12:13], v[14:15], v[106:107] op_sel_hi:[0,1,1]
	v_readlane_b32 s36, v6, 2
	v_pk_fma_f32 v[104:105], s[36:37], v[16:17], v[104:105] op_sel_hi:[0,1,1]
	v_pk_fma_f32 v[106:107], s[36:37], v[18:19], v[106:107] op_sel_hi:[0,1,1]
	v_readlane_b32 s12, v6, 3
	v_pk_fma_f32 v[104:105], s[12:13], v[20:21], v[104:105] op_sel_hi:[0,1,1]
	v_pk_fma_f32 v[106:107], s[12:13], v[22:23], v[106:107] op_sel_hi:[0,1,1]
	v_readlane_b32 s36, v6, 4
	v_pk_fma_f32 v[104:105], s[36:37], v[24:25], v[104:105] op_sel_hi:[0,1,1]
	v_pk_fma_f32 v[106:107], s[36:37], v[26:27], v[106:107] op_sel_hi:[0,1,1]
	v_readlane_b32 s12, v6, 5
	v_pk_fma_f32 v[104:105], s[12:13], v[28:29], v[104:105] op_sel_hi:[0,1,1]
	v_pk_fma_f32 v[106:107], s[12:13], v[30:31], v[106:107] op_sel_hi:[0,1,1]
	v_readlane_b32 s36, v6, 6
	v_pk_fma_f32 v[104:105], s[36:37], v[32:33], v[104:105] op_sel_hi:[0,1,1]
	v_pk_fma_f32 v[106:107], s[36:37], v[34:35], v[106:107] op_sel_hi:[0,1,1]
	v_readlane_b32 s12, v6, 7
	v_pk_fma_f32 v[104:105], s[12:13], v[36:37], v[104:105] op_sel_hi:[0,1,1]
	v_pk_fma_f32 v[106:107], s[12:13], v[38:39], v[106:107] op_sel_hi:[0,1,1]
	s_add_i32 s47, s45, 4
	s_min_u32 s47, s47, s30
	s_add_i32 s50, s45, -4
	s_max_i32 s50, s50, 0
	s_sub_i32 s47, s47, s50
	v_cvt_f32_i32_e32 v116, s47
	v_div_scale_f32 v120, s[12:13], v116, v116, 1.0
	v_rcp_f32_e32 v121, v120
	v_div_scale_f32 v122, vcc, 1.0, v116, 1.0
	s_nop 0
	v_fma_f32 v124, -v120, v121, 1.0
	v_fmac_f32_e32 v121, v124, v121
	v_mul_f32_e32 v123, v122, v121
	v_fma_f32 v124, -v120, v123, v122
	v_fmac_f32_e32 v123, v124, v121
	v_fma_f32 v120, -v120, v123, v122
	v_div_fmas_f32 v120, v120, v121, v123
	v_div_fixup_f32 v118, v120, v116, 1.0
	v_readlane_b32 s36, v6, 4
	v_pk_mul_f32 v[112:113], s[36:37], v[24:25] op_sel_hi:[0,1]
	v_pk_mul_f32 v[114:115], s[36:37], v[26:27] op_sel_hi:[0,1]
	v_pk_fma_f32 v[112:113], v[118:119], v[104:105], v[112:113] op_sel_hi:[0,1,1] neg_lo:[0,0,1] neg_hi:[0,0,1]
	v_pk_fma_f32 v[114:115], v[118:119], v[106:107], v[114:115] op_sel_hi:[0,1,1] neg_lo:[0,0,1] neg_hi:[0,0,1]
	v_pk_mul_f32 v[112:113], v[108:109], v[112:113]
	v_pk_mul_f32 v[114:115], v[110:111], v[114:115]
	v_cvt_pk_bf16_f32 v128, v112, v113
	v_cvt_pk_bf16_f32 v129, v114, v115
	s_add_i32 s47, s28, s40
	s_add_i32 s47, s47, 0
	s_lshl_b32 s47, s47, 11
	v_add_u32_e32 v130, s47, v7
	global_store_dwordx2 v130, v[128:129], s[22:23]
	v_readlane_b32 s36, v6, 0
	v_readlane_b32 s12, v6, 8
	v_pk_mul_f32 v[112:113], s[36:37], v[8:9] op_sel_hi:[0,1]
	v_pk_mul_f32 v[114:115], s[36:37], v[10:11] op_sel_hi:[0,1]
	v_pk_fma_f32 v[112:113], s[12:13], v[40:41], v[112:113] op_sel_hi:[0,1,1] neg_lo:[0,0,1] neg_hi:[0,0,1]
	v_pk_fma_f32 v[114:115], s[12:13], v[42:43], v[114:115] op_sel_hi:[0,1,1] neg_lo:[0,0,1] neg_hi:[0,0,1]
	v_pk_add_f32 v[104:105], v[104:105], v[112:113]
	v_pk_add_f32 v[106:107], v[106:107], v[114:115]
	s_add_i32 s47, s45, 5
	s_min_u32 s47, s47, s30
	s_add_i32 s50, s45, -3
	s_max_i32 s50, s50, 0
	s_sub_i32 s47, s47, s50
	v_cvt_f32_i32_e32 v116, s47
	v_div_scale_f32 v120, s[12:13], v116, v116, 1.0
	v_rcp_f32_e32 v121, v120
	v_div_scale_f32 v122, vcc, 1.0, v116, 1.0
	s_nop 0
	v_fma_f32 v124, -v120, v121, 1.0
	v_fmac_f32_e32 v121, v124, v121
	v_mul_f32_e32 v123, v122, v121
	v_fma_f32 v124, -v120, v123, v122
	v_fmac_f32_e32 v123, v124, v121
	v_fma_f32 v120, -v120, v123, v122
	v_div_fmas_f32 v120, v120, v121, v123
	v_div_fixup_f32 v118, v120, v116, 1.0
	v_readlane_b32 s36, v6, 5
	v_pk_mul_f32 v[112:113], s[36:37], v[28:29] op_sel_hi:[0,1]
	v_pk_mul_f32 v[114:115], s[36:37], v[30:31] op_sel_hi:[0,1]
	v_pk_fma_f32 v[112:113], v[118:119], v[104:105], v[112:113] op_sel_hi:[0,1,1] neg_lo:[0,0,1] neg_hi:[0,0,1]
	v_pk_fma_f32 v[114:115], v[118:119], v[106:107], v[114:115] op_sel_hi:[0,1,1] neg_lo:[0,0,1] neg_hi:[0,0,1]
	v_pk_mul_f32 v[112:113], v[108:109], v[112:113]
	v_pk_mul_f32 v[114:115], v[110:111], v[114:115]
	v_cvt_pk_bf16_f32 v128, v112, v113
	v_cvt_pk_bf16_f32 v129, v114, v115
	s_add_i32 s47, s28, s40
	s_add_i32 s47, s47, 1
	s_lshl_b32 s47, s47, 11
	v_add_u32_e32 v130, s47, v7
	global_store_dwordx2 v130, v[128:129], s[22:23]
	v_readlane_b32 s36, v6, 1
	v_readlane_b32 s12, v6, 9
	v_pk_mul_f32 v[112:113], s[36:37], v[12:13] op_sel_hi:[0,1]
	v_pk_mul_f32 v[114:115], s[36:37], v[14:15] op_sel_hi:[0,1]
	v_pk_fma_f32 v[112:113], s[12:13], v[44:45], v[112:113] op_sel_hi:[0,1,1] neg_lo:[0,0,1] neg_hi:[0,0,1]
	v_pk_fma_f32 v[114:115], s[12:13], v[46:47], v[114:115] op_sel_hi:[0,1,1] neg_lo:[0,0,1] neg_hi:[0,0,1]
	v_pk_add_f32 v[104:105], v[104:105], v[112:113]
	v_pk_add_f32 v[106:107], v[106:107], v[114:115]
	s_add_i32 s47, s45, 6
	s_min_u32 s47, s47, s30
	s_add_i32 s50, s45, -2
	s_max_i32 s50, s50, 0
	s_sub_i32 s47, s47, s50
	v_cvt_f32_i32_e32 v116, s47
	v_div_scale_f32 v120, s[12:13], v116, v116, 1.0
	v_rcp_f32_e32 v121, v120
	v_div_scale_f32 v122, vcc, 1.0, v116, 1.0
	s_nop 0
	v_fma_f32 v124, -v120, v121, 1.0
	v_fmac_f32_e32 v121, v124, v121
	v_mul_f32_e32 v123, v122, v121
	v_fma_f32 v124, -v120, v123, v122
	v_fmac_f32_e32 v123, v124, v121
	v_fma_f32 v120, -v120, v123, v122
	v_div_fmas_f32 v120, v120, v121, v123
	v_div_fixup_f32 v118, v120, v116, 1.0
	v_readlane_b32 s36, v6, 6
	v_pk_mul_f32 v[112:113], s[36:37], v[32:33] op_sel_hi:[0,1]
	v_pk_mul_f32 v[114:115], s[36:37], v[34:35] op_sel_hi:[0,1]
	v_pk_fma_f32 v[112:113], v[118:119], v[104:105], v[112:113] op_sel_hi:[0,1,1] neg_lo:[0,0,1] neg_hi:[0,0,1]
	v_pk_fma_f32 v[114:115], v[118:119], v[106:107], v[114:115] op_sel_hi:[0,1,1] neg_lo:[0,0,1] neg_hi:[0,0,1]
	v_pk_mul_f32 v[112:113], v[108:109], v[112:113]
	v_pk_mul_f32 v[114:115], v[110:111], v[114:115]
	v_cvt_pk_bf16_f32 v128, v112, v113
	v_cvt_pk_bf16_f32 v129, v114, v115
	s_add_i32 s47, s28, s40
	s_add_i32 s47, s47, 2
	s_lshl_b32 s47, s47, 11
	v_add_u32_e32 v130, s47, v7
	global_store_dwordx2 v130, v[128:129], s[22:23]
	v_readlane_b32 s36, v6, 2
	v_readlane_b32 s12, v6, 10
	v_pk_mul_f32 v[112:113], s[36:37], v[16:17] op_sel_hi:[0,1]
	v_pk_mul_f32 v[114:115], s[36:37], v[18:19] op_sel_hi:[0,1]
	v_pk_fma_f32 v[112:113], s[12:13], v[48:49], v[112:113] op_sel_hi:[0,1,1] neg_lo:[0,0,1] neg_hi:[0,0,1]
	v_pk_fma_f32 v[114:115], s[12:13], v[50:51], v[114:115] op_sel_hi:[0,1,1] neg_lo:[0,0,1] neg_hi:[0,0,1]
	v_pk_add_f32 v[104:105], v[104:105], v[112:113]
	v_pk_add_f32 v[106:107], v[106:107], v[114:115]
	s_add_i32 s47, s45, 7
	s_min_u32 s47, s47, s30
	s_add_i32 s50, s45, -1
	s_max_i32 s50, s50, 0
	s_sub_i32 s47, s47, s50
	v_cvt_f32_i32_e32 v116, s47
	v_div_scale_f32 v120, s[12:13], v116, v116, 1.0
	v_rcp_f32_e32 v121, v120
	v_div_scale_f32 v122, vcc, 1.0, v116, 1.0
	s_nop 0
	v_fma_f32 v124, -v120, v121, 1.0
	v_fmac_f32_e32 v121, v124, v121
	v_mul_f32_e32 v123, v122, v121
	v_fma_f32 v124, -v120, v123, v122
	v_fmac_f32_e32 v123, v124, v121
	v_fma_f32 v120, -v120, v123, v122
	v_div_fmas_f32 v120, v120, v121, v123
	v_div_fixup_f32 v118, v120, v116, 1.0
	v_readlane_b32 s36, v6, 7
	v_pk_mul_f32 v[112:113], s[36:37], v[36:37] op_sel_hi:[0,1]
	v_pk_mul_f32 v[114:115], s[36:37], v[38:39] op_sel_hi:[0,1]
	v_pk_fma_f32 v[112:113], v[118:119], v[104:105], v[112:113] op_sel_hi:[0,1,1] neg_lo:[0,0,1] neg_hi:[0,0,1]
	v_pk_fma_f32 v[114:115], v[118:119], v[106:107], v[114:115] op_sel_hi:[0,1,1] neg_lo:[0,0,1] neg_hi:[0,0,1]
	v_pk_mul_f32 v[112:113], v[108:109], v[112:113]
	v_pk_mul_f32 v[114:115], v[110:111], v[114:115]
	v_cvt_pk_bf16_f32 v128, v112, v113
	v_cvt_pk_bf16_f32 v129, v114, v115
	s_add_i32 s47, s28, s40
	s_add_i32 s47, s47, 3
	s_lshl_b32 s47, s47, 11
	v_add_u32_e32 v130, s47, v7
	global_store_dwordx2 v130, v[128:129], s[22:23]
	s_lshl_b32 s40, s34, 3
	s_add_i32 s40, s40, 4
	s_lshl_b32 s41, s40, 10
	v_add_u32_e32 v4, s41, v1
	ds_read_b128 v[8:11], v4
	ds_read_b128 v[12:15], v4 offset:1024
	ds_read_b128 v[16:19], v4 offset:2048
	ds_read_b128 v[20:23], v4 offset:3072
	ds_read_b128 v[24:27], v4 offset:4096
	ds_read_b128 v[28:31], v4 offset:5120
	ds_read_b128 v[32:35], v4 offset:6144
	ds_read_b128 v[36:39], v4 offset:7168
	ds_read_b128 v[40:43], v4 offset:8192
	ds_read_b128 v[44:47], v4 offset:9216
	ds_read_b128 v[48:51], v4 offset:10240
	s_add_i32 s41, s31, s40
	s_sub_i32 s41, s41, 4
	v_add_u32_e32 v5, s41, v0
	v_cmp_le_i32_e64 s[36:37], 0, v5
	v_cmp_gt_i32_e64 s[12:13], s30, v5
	s_and_b64 s[36:37], s[36:37], s[12:13]
	v_max_i32_e32 v5, 0, v5
	s_add_i32 s41, s30, -1
	v_min_i32_e32 v5, s41, v5
	v_add_u32_e32 v5, s29, v5
	v_lshlrev_b32_e32 v5, 2, v5
	global_load_dword v6, v5, s[18:19]
	s_waitcnt vmcnt(0)
	v_cndmask_b32_e64 v6, 0, v6, s[36:37]
	s_add_i32 s45, s31, s40
	s_waitcnt lgkmcnt(0)
	v_readlane_b32 s36, v6, 0
	v_pk_fma_f32 v[104:105], s[36:37], v[8:9], 0 op_sel_hi:[0,1,0]
	v_pk_fma_f32 v[106:107], s[36:37], v[10:11], 0 op_sel_hi:[0,1,0]
	v_readlane_b32 s12, v6, 1
	v_pk_fma_f32 v[104:105], s[12:13], v[12:13], v[104:105] op_sel_hi:[0,1,1]
	v_pk_fma_f32 v[106:107], s[12:13], v[14:15], v[106:107] op_sel_hi:[0,1,1]
	v_readlane_b32 s36, v6, 2
	v_pk_fma_f32 v[104:105], s[36:37], v[16:17], v[104:105] op_sel_hi:[0,1,1]
	v_pk_fma_f32 v[106:107], s[36:37], v[18:19], v[106:107] op_sel_hi:[0,1,1]
	v_readlane_b32 s12, v6, 3
	v_pk_fma_f32 v[104:105], s[12:13], v[20:21], v[104:105] op_sel_hi:[0,1,1]
	v_pk_fma_f32 v[106:107], s[12:13], v[22:23], v[106:107] op_sel_hi:[0,1,1]
	v_readlane_b32 s36, v6, 4
	v_pk_fma_f32 v[104:105], s[36:37], v[24:25], v[104:105] op_sel_hi:[0,1,1]
	v_pk_fma_f32 v[106:107], s[36:37], v[26:27], v[106:107] op_sel_hi:[0,1,1]
	v_readlane_b32 s12, v6, 5
	v_pk_fma_f32 v[104:105], s[12:13], v[28:29], v[104:105] op_sel_hi:[0,1,1]
	v_pk_fma_f32 v[106:107], s[12:13], v[30:31], v[106:107] op_sel_hi:[0,1,1]
	v_readlane_b32 s36, v6, 6
	v_pk_fma_f32 v[104:105], s[36:37], v[32:33], v[104:105] op_sel_hi:[0,1,1]
	v_pk_fma_f32 v[106:107], s[36:37], v[34:35], v[106:107] op_sel_hi:[0,1,1]
	v_readlane_b32 s12, v6, 7
	v_pk_fma_f32 v[104:105], s[12:13], v[36:37], v[104:105] op_sel_hi:[0,1,1]
	v_pk_fma_f32 v[106:107], s[12:13], v[38:39], v[106:107] op_sel_hi:[0,1,1]
	s_add_i32 s47, s45, 4
	s_min_u32 s47, s47, s30
	s_add_i32 s50, s45, -4
	s_max_i32 s50, s50, 0
	s_sub_i32 s47, s47, s50
	v_cvt_f32_i32_e32 v116, s47
	v_div_scale_f32 v120, s[12:13], v116, v116, 1.0
	v_rcp_f32_e32 v121, v120
	v_div_scale_f32 v122, vcc, 1.0, v116, 1.0
	s_nop 0
	v_fma_f32 v124, -v120, v121, 1.0
	v_fmac_f32_e32 v121, v124, v121
	v_mul_f32_e32 v123, v122, v121
	v_fma_f32 v124, -v120, v123, v122
	v_fmac_f32_e32 v123, v124, v121
	v_fma_f32 v120, -v120, v123, v122
	v_div_fmas_f32 v120, v120, v121, v123
	v_div_fixup_f32 v118, v120, v116, 1.0
	v_readlane_b32 s36, v6, 4
	v_pk_mul_f32 v[112:113], s[36:37], v[24:25] op_sel_hi:[0,1]
	v_pk_mul_f32 v[114:115], s[36:37], v[26:27] op_sel_hi:[0,1]
	v_pk_fma_f32 v[112:113], v[118:119], v[104:105], v[112:113] op_sel_hi:[0,1,1] neg_lo:[0,0,1] neg_hi:[0,0,1]
	v_pk_fma_f32 v[114:115], v[118:119], v[106:107], v[114:115] op_sel_hi:[0,1,1] neg_lo:[0,0,1] neg_hi:[0,0,1]
	v_pk_mul_f32 v[112:113], v[108:109], v[112:113]
	v_pk_mul_f32 v[114:115], v[110:111], v[114:115]
	v_cvt_pk_bf16_f32 v128, v112, v113
	v_cvt_pk_bf16_f32 v129, v114, v115
	s_add_i32 s47, s28, s40
	s_add_i32 s47, s47, 0
	s_lshl_b32 s47, s47, 11
	v_add_u32_e32 v130, s47, v7
	global_store_dwordx2 v130, v[128:129], s[22:23]
	v_readlane_b32 s36, v6, 0
	v_readlane_b32 s12, v6, 8
	v_pk_mul_f32 v[112:113], s[36:37], v[8:9] op_sel_hi:[0,1]
	v_pk_mul_f32 v[114:115], s[36:37], v[10:11] op_sel_hi:[0,1]
	v_pk_fma_f32 v[112:113], s[12:13], v[40:41], v[112:113] op_sel_hi:[0,1,1] neg_lo:[0,0,1] neg_hi:[0,0,1]
	v_pk_fma_f32 v[114:115], s[12:13], v[42:43], v[114:115] op_sel_hi:[0,1,1] neg_lo:[0,0,1] neg_hi:[0,0,1]
	v_pk_add_f32 v[104:105], v[104:105], v[112:113]
	v_pk_add_f32 v[106:107], v[106:107], v[114:115]
	s_add_i32 s47, s45, 5
	s_min_u32 s47, s47, s30
	s_add_i32 s50, s45, -3
	s_max_i32 s50, s50, 0
	s_sub_i32 s47, s47, s50
	v_cvt_f32_i32_e32 v116, s47
	v_div_scale_f32 v120, s[12:13], v116, v116, 1.0
	v_rcp_f32_e32 v121, v120
	v_div_scale_f32 v122, vcc, 1.0, v116, 1.0
	s_nop 0
	v_fma_f32 v124, -v120, v121, 1.0
	v_fmac_f32_e32 v121, v124, v121
	v_mul_f32_e32 v123, v122, v121
	v_fma_f32 v124, -v120, v123, v122
	v_fmac_f32_e32 v123, v124, v121
	v_fma_f32 v120, -v120, v123, v122
	v_div_fmas_f32 v120, v120, v121, v123
	v_div_fixup_f32 v118, v120, v116, 1.0
	v_readlane_b32 s36, v6, 5
	v_pk_mul_f32 v[112:113], s[36:37], v[28:29] op_sel_hi:[0,1]
	v_pk_mul_f32 v[114:115], s[36:37], v[30:31] op_sel_hi:[0,1]
	v_pk_fma_f32 v[112:113], v[118:119], v[104:105], v[112:113] op_sel_hi:[0,1,1] neg_lo:[0,0,1] neg_hi:[0,0,1]
	v_pk_fma_f32 v[114:115], v[118:119], v[106:107], v[114:115] op_sel_hi:[0,1,1] neg_lo:[0,0,1] neg_hi:[0,0,1]
	v_pk_mul_f32 v[112:113], v[108:109], v[112:113]
	v_pk_mul_f32 v[114:115], v[110:111], v[114:115]
	v_cvt_pk_bf16_f32 v128, v112, v113
	v_cvt_pk_bf16_f32 v129, v114, v115
	s_add_i32 s47, s28, s40
	s_add_i32 s47, s47, 1
	s_lshl_b32 s47, s47, 11
	v_add_u32_e32 v130, s47, v7
	global_store_dwordx2 v130, v[128:129], s[22:23]
	v_readlane_b32 s36, v6, 1
	v_readlane_b32 s12, v6, 9
	v_pk_mul_f32 v[112:113], s[36:37], v[12:13] op_sel_hi:[0,1]
	v_pk_mul_f32 v[114:115], s[36:37], v[14:15] op_sel_hi:[0,1]
	v_pk_fma_f32 v[112:113], s[12:13], v[44:45], v[112:113] op_sel_hi:[0,1,1] neg_lo:[0,0,1] neg_hi:[0,0,1]
	v_pk_fma_f32 v[114:115], s[12:13], v[46:47], v[114:115] op_sel_hi:[0,1,1] neg_lo:[0,0,1] neg_hi:[0,0,1]
	v_pk_add_f32 v[104:105], v[104:105], v[112:113]
	v_pk_add_f32 v[106:107], v[106:107], v[114:115]
	s_add_i32 s47, s45, 6
	s_min_u32 s47, s47, s30
	s_add_i32 s50, s45, -2
	s_max_i32 s50, s50, 0
	s_sub_i32 s47, s47, s50
	v_cvt_f32_i32_e32 v116, s47
	v_div_scale_f32 v120, s[12:13], v116, v116, 1.0
	v_rcp_f32_e32 v121, v120
	v_div_scale_f32 v122, vcc, 1.0, v116, 1.0
	s_nop 0
	v_fma_f32 v124, -v120, v121, 1.0
	v_fmac_f32_e32 v121, v124, v121
	v_mul_f32_e32 v123, v122, v121
	v_fma_f32 v124, -v120, v123, v122
	v_fmac_f32_e32 v123, v124, v121
	v_fma_f32 v120, -v120, v123, v122
	v_div_fmas_f32 v120, v120, v121, v123
	v_div_fixup_f32 v118, v120, v116, 1.0
	v_readlane_b32 s36, v6, 6
	v_pk_mul_f32 v[112:113], s[36:37], v[32:33] op_sel_hi:[0,1]
	v_pk_mul_f32 v[114:115], s[36:37], v[34:35] op_sel_hi:[0,1]
	v_pk_fma_f32 v[112:113], v[118:119], v[104:105], v[112:113] op_sel_hi:[0,1,1] neg_lo:[0,0,1] neg_hi:[0,0,1]
	v_pk_fma_f32 v[114:115], v[118:119], v[106:107], v[114:115] op_sel_hi:[0,1,1] neg_lo:[0,0,1] neg_hi:[0,0,1]
	v_pk_mul_f32 v[112:113], v[108:109], v[112:113]
	v_pk_mul_f32 v[114:115], v[110:111], v[114:115]
	v_cvt_pk_bf16_f32 v128, v112, v113
	v_cvt_pk_bf16_f32 v129, v114, v115
	s_add_i32 s47, s28, s40
	s_add_i32 s47, s47, 2
	s_lshl_b32 s47, s47, 11
	v_add_u32_e32 v130, s47, v7
	global_store_dwordx2 v130, v[128:129], s[22:23]
	v_readlane_b32 s36, v6, 2
	v_readlane_b32 s12, v6, 10
	v_pk_mul_f32 v[112:113], s[36:37], v[16:17] op_sel_hi:[0,1]
	v_pk_mul_f32 v[114:115], s[36:37], v[18:19] op_sel_hi:[0,1]
	v_pk_fma_f32 v[112:113], s[12:13], v[48:49], v[112:113] op_sel_hi:[0,1,1] neg_lo:[0,0,1] neg_hi:[0,0,1]
	v_pk_fma_f32 v[114:115], s[12:13], v[50:51], v[114:115] op_sel_hi:[0,1,1] neg_lo:[0,0,1] neg_hi:[0,0,1]
	v_pk_add_f32 v[104:105], v[104:105], v[112:113]
	v_pk_add_f32 v[106:107], v[106:107], v[114:115]
	s_add_i32 s47, s45, 7
	s_min_u32 s47, s47, s30
	s_add_i32 s50, s45, -1
	s_max_i32 s50, s50, 0
	s_sub_i32 s47, s47, s50
	v_cvt_f32_i32_e32 v116, s47
	v_div_scale_f32 v120, s[12:13], v116, v116, 1.0
	v_rcp_f32_e32 v121, v120
	v_div_scale_f32 v122, vcc, 1.0, v116, 1.0
	s_nop 0
	v_fma_f32 v124, -v120, v121, 1.0
	v_fmac_f32_e32 v121, v124, v121
	v_mul_f32_e32 v123, v122, v121
	v_fma_f32 v124, -v120, v123, v122
	v_fmac_f32_e32 v123, v124, v121
	v_fma_f32 v120, -v120, v123, v122
	v_div_fmas_f32 v120, v120, v121, v123
	v_div_fixup_f32 v118, v120, v116, 1.0
	v_readlane_b32 s36, v6, 7
	v_pk_mul_f32 v[112:113], s[36:37], v[36:37] op_sel_hi:[0,1]
	v_pk_mul_f32 v[114:115], s[36:37], v[38:39] op_sel_hi:[0,1]
	v_pk_fma_f32 v[112:113], v[118:119], v[104:105], v[112:113] op_sel_hi:[0,1,1] neg_lo:[0,0,1] neg_hi:[0,0,1]
	v_pk_fma_f32 v[114:115], v[118:119], v[106:107], v[114:115] op_sel_hi:[0,1,1] neg_lo:[0,0,1] neg_hi:[0,0,1]
	v_pk_mul_f32 v[112:113], v[108:109], v[112:113]
	v_pk_mul_f32 v[114:115], v[110:111], v[114:115]
	v_cvt_pk_bf16_f32 v128, v112, v113
	v_cvt_pk_bf16_f32 v129, v114, v115
	s_add_i32 s47, s28, s40
	s_add_i32 s47, s47, 3
	s_lshl_b32 s47, s47, 11
	v_add_u32_e32 v130, s47, v7
	global_store_dwordx2 v130, v[128:129], s[22:23]
	s_branch .Lpz_next
.Lpz_c1:
	s_lshl_b32 s40, s34, 3
	s_lshl_b32 s41, s40, 10
	v_add_u32_e32 v4, s41, v1
	ds_read_b128 v[8:11], v4
	ds_read_b128 v[12:15], v4 offset:1024
	ds_read_b128 v[16:19], v4 offset:2048
	ds_read_b128 v[20:23], v4 offset:3072
	ds_read_b128 v[24:27], v4 offset:4096
	ds_read_b128 v[28:31], v4 offset:5120
	ds_read_b128 v[32:35], v4 offset:6144
	s_add_i32 s41, s31, s40
	s_sub_i32 s41, s41, 2
	v_add_u32_e32 v5, s41, v0
	v_cmp_le_i32_e64 s[36:37], 0, v5
	v_cmp_gt_i32_e64 s[12:13], s30, v5
	s_and_b64 s[36:37], s[36:37], s[12:13]
	v_max_i32_e32 v5, 0, v5
	s_add_i32 s41, s30, -1
	v_min_i32_e32 v5, s41, v5
	v_add_u32_e32 v5, s29, v5
	v_lshlrev_b32_e32 v5, 2, v5
	global_load_dword v6, v5, s[18:19]
	s_waitcnt vmcnt(0)
	v_cndmask_b32_e64 v6, 0, v6, s[36:37]
	s_add_i32 s45, s31, s40
	s_waitcnt lgkmcnt(0)
	v_readlane_b32 s36, v6, 0
	v_pk_fma_f32 v[104:105], s[36:37], v[8:9], 0 op_sel_hi:[0,1,0]
	v_pk_fma_f32 v[106:107], s[36:37], v[10:11], 0 op_sel_hi:[0,1,0]
	v_readlane_b32 s12, v6, 1
	v_pk_fma_f32 v[104:105], s[12:13], v[12:13], v[104:105] op_sel_hi:[0,1,1]
	v_pk_fma_f32 v[106:107], s[12:13], v[14:15], v[106:107] op_sel_hi:[0,1,1]
	v_readlane_b32 s36, v6, 2
	v_pk_fma_f32 v[104:105], s[36:37], v[16:17], v[104:105] op_sel_hi:[0,1,1]
	v_pk_fma_f32 v[106:107], s[36:37], v[18:19], v[106:107] op_sel_hi:[0,1,1]
	v_readlane_b32 s12, v6, 3
	v_pk_fma_f32 v[104:105], s[12:13], v[20:21], v[104:105] op_sel_hi:[0,1,1]
	v_pk_fma_f32 v[106:107], s[12:13], v[22:23], v[106:107] op_sel_hi:[0,1,1]
	s_add_i32 s47, s45, 2
	s_min_u32 s47, s47, s30
	s_add_i32 s50, s45, -2
	s_max_i32 s50, s50, 0
	s_sub_i32 s47, s47, s50
	v_cvt_f32_i32_e32 v116, s47
	v_div_scale_f32 v120, s[12:13], v116, v116, 1.0
	v_rcp_f32_e32 v121, v120
	v_div_scale_f32 v122, vcc, 1.0, v116, 1.0
	s_nop 0
	v_fma_f32 v124, -v120, v121, 1.0
	v_fmac_f32_e32 v121, v124, v121
	v_mul_f32_e32 v123, v122, v121
	v_fma_f32 v124, -v120, v123, v122
	v_fmac_f32_e32 v123, v124, v121
	v_fma_f32 v120, -v120, v123, v122
	v_div_fmas_f32 v120, v120, v121, v123
	v_div_fixup_f32 v118, v120, v116, 1.0
	v_readlane_b32 s36, v6, 2
	v_pk_mul_f32 v[112:113], s[36:37], v[16:17] op_sel_hi:[0,1]
	v_pk_mul_f32 v[114:115], s[36:37], v[18:19] op_sel_hi:[0,1]
	v_pk_fma_f32 v[112:113], v[118:119], v[104:105], v[112:113] op_sel_hi:[0,1,1] neg_lo:[0,0,1] neg_hi:[0,0,1]
	v_pk_fma_f32 v[114:115], v[118:119], v[106:107], v[114:115] op_sel_hi:[0,1,1] neg_lo:[0,0,1] neg_hi:[0,0,1]
	v_pk_mul_f32 v[112:113], v[108:109], v[112:113]
	v_pk_mul_f32 v[114:115], v[110:111], v[114:115]
	v_cvt_pk_bf16_f32 v128, v112, v113
	v_cvt_pk_bf16_f32 v129, v114, v115
	s_add_i32 s47, s28, s40
	s_add_i32 s47, s47, 0
	s_lshl_b32 s47, s47, 11
	v_add_u32_e32 v130, s47, v7
	global_store_dwordx2 v130, v[128:129], s[22:23]
	v_readlane_b32 s36, v6, 0
	v_readlane_b32 s12, v6, 4
	v_pk_mul_f32 v[112:113], s[36:37], v[8:9] op_sel_hi:[0,1]
	v_pk_mul_f32 v[114:115], s[36:37], v[10:11] op_sel_hi:[0,1]
	v_pk_fma_f32 v[112:113], s[12:13], v[24:25], v[112:113] op_sel_hi:[0,1,1] neg_lo:[0,0,1] neg_hi:[0,0,1]
	v_pk_fma_f32 v[114:115], s[12:13], v[26:27], v[114:115] op_sel_hi:[0,1,1] neg_lo:[0,0,1] neg_hi:[0,0,1]
	v_pk_add_f32 v[104:105], v[104:105], v[112:113]
	v_pk_add_f32 v[106:107], v[106:107], v[114:115]
	s_add_i32 s47, s45, 3
	s_min_u32 s47, s47, s30
	s_add_i32 s50, s45, -1
	s_max_i32 s50, s50, 0
	s_sub_i32 s47, s47, s50
	v_cvt_f32_i32_e32 v116, s47
	v_div_scale_f32 v120, s[12:13], v116, v116, 1.0
	v_rcp_f32_e32 v121, v120
	v_div_scale_f32 v122, vcc, 1.0, v116, 1.0
	s_nop 0
	v_fma_f32 v124, -v120, v121, 1.0
	v_fmac_f32_e32 v121, v124, v121
	v_mul_f32_e32 v123, v122, v121
	v_fma_f32 v124, -v120, v123, v122
	v_fmac_f32_e32 v123, v124, v121
	v_fma_f32 v120, -v120, v123, v122
	v_div_fmas_f32 v120, v120, v121, v123
	v_div_fixup_f32 v118, v120, v116, 1.0
	v_readlane_b32 s36, v6, 3
	v_pk_mul_f32 v[112:113], s[36:37], v[20:21] op_sel_hi:[0,1]
	v_pk_mul_f32 v[114:115], s[36:37], v[22:23] op_sel_hi:[0,1]
	v_pk_fma_f32 v[112:113], v[118:119], v[104:105], v[112:113] op_sel_hi:[0,1,1] neg_lo:[0,0,1] neg_hi:[0,0,1]
	v_pk_fma_f32 v[114:115], v[118:119], v[106:107], v[114:115] op_sel_hi:[0,1,1] neg_lo:[0,0,1] neg_hi:[0,0,1]
	v_pk_mul_f32 v[112:113], v[108:109], v[112:113]
	v_pk_mul_f32 v[114:115], v[110:111], v[114:115]
	v_cvt_pk_bf16_f32 v128, v112, v113
	v_cvt_pk_bf16_f32 v129, v114, v115
	s_add_i32 s47, s28, s40
	s_add_i32 s47, s47, 1
	s_lshl_b32 s47, s47, 11
	v_add_u32_e32 v130, s47, v7
	global_store_dwordx2 v130, v[128:129], s[22:23]
	v_readlane_b32 s36, v6, 1
	v_readlane_b32 s12, v6, 5
	v_pk_mul_f32 v[112:113], s[36:37], v[12:13] op_sel_hi:[0,1]
	v_pk_mul_f32 v[114:115], s[36:37], v[14:15] op_sel_hi:[0,1]
	v_pk_fma_f32 v[112:113], s[12:13], v[28:29], v[112:113] op_sel_hi:[0,1,1] neg_lo:[0,0,1] neg_hi:[0,0,1]
	v_pk_fma_f32 v[114:115], s[12:13], v[30:31], v[114:115] op_sel_hi:[0,1,1] neg_lo:[0,0,1] neg_hi:[0,0,1]
	v_pk_add_f32 v[104:105], v[104:105], v[112:113]
	v_pk_add_f32 v[106:107], v[106:107], v[114:115]
	s_add_i32 s47, s45, 4
	s_min_u32 s47, s47, s30
	s_add_i32 s50, s45, 0
	s_max_i32 s50, s50, 0
	s_sub_i32 s47, s47, s50
	v_cvt_f32_i32_e32 v116, s47
	v_div_scale_f32 v120, s[12:13], v116, v116, 1.0
	v_rcp_f32_e32 v121, v120
	v_div_scale_f32 v122, vcc, 1.0, v116, 1.0
	s_nop 0
	v_fma_f32 v124, -v120, v121, 1.0
	v_fmac_f32_e32 v121, v124, v121
	v_mul_f32_e32 v123, v122, v121
	v_fma_f32 v124, -v120, v123, v122
	v_fmac_f32_e32 v123, v124, v121
	v_fma_f32 v120, -v120, v123, v122
	v_div_fmas_f32 v120, v120, v121, v123
	v_div_fixup_f32 v118, v120, v116, 1.0
	v_readlane_b32 s36, v6, 4
	v_pk_mul_f32 v[112:113], s[36:37], v[24:25] op_sel_hi:[0,1]
	v_pk_mul_f32 v[114:115], s[36:37], v[26:27] op_sel_hi:[0,1]
	v_pk_fma_f32 v[112:113], v[118:119], v[104:105], v[112:113] op_sel_hi:[0,1,1] neg_lo:[0,0,1] neg_hi:[0,0,1]
	v_pk_fma_f32 v[114:115], v[118:119], v[106:107], v[114:115] op_sel_hi:[0,1,1] neg_lo:[0,0,1] neg_hi:[0,0,1]
	v_pk_mul_f32 v[112:113], v[108:109], v[112:113]
	v_pk_mul_f32 v[114:115], v[110:111], v[114:115]
	v_cvt_pk_bf16_f32 v128, v112, v113
	v_cvt_pk_bf16_f32 v129, v114, v115
	s_add_i32 s47, s28, s40
	s_add_i32 s47, s47, 2
	s_lshl_b32 s47, s47, 11
	v_add_u32_e32 v130, s47, v7
	global_store_dwordx2 v130, v[128:129], s[22:23]
	v_readlane_b32 s36, v6, 2
	v_readlane_b32 s12, v6, 6
	v_pk_mul_f32 v[112:113], s[36:37], v[16:17] op_sel_hi:[0,1]
	v_pk_mul_f32 v[114:115], s[36:37], v[18:19] op_sel_hi:[0,1]
	v_pk_fma_f32 v[112:113], s[12:13], v[32:33], v[112:113] op_sel_hi:[0,1,1] neg_lo:[0,0,1] neg_hi:[0,0,1]
	v_pk_fma_f32 v[114:115], s[12:13], v[34:35], v[114:115] op_sel_hi:[0,1,1] neg_lo:[0,0,1] neg_hi:[0,0,1]
	v_pk_add_f32 v[104:105], v[104:105], v[112:113]
	v_pk_add_f32 v[106:107], v[106:107], v[114:115]
	s_add_i32 s47, s45, 5
	s_min_u32 s47, s47, s30
	s_add_i32 s50, s45, 1
	s_max_i32 s50, s50, 0
	s_sub_i32 s47, s47, s50
	v_cvt_f32_i32_e32 v116, s47
	v_div_scale_f32 v120, s[12:13], v116, v116, 1.0
	v_rcp_f32_e32 v121, v120
	v_div_scale_f32 v122, vcc, 1.0, v116, 1.0
	s_nop 0
	v_fma_f32 v124, -v120, v121, 1.0
	v_fmac_f32_e32 v121, v124, v121
	v_mul_f32_e32 v123, v122, v121
	v_fma_f32 v124, -v120, v123, v122
	v_fmac_f32_e32 v123, v124, v121
	v_fma_f32 v120, -v120, v123, v122
	v_div_fmas_f32 v120, v120, v121, v123
	v_div_fixup_f32 v118, v120, v116, 1.0
	v_readlane_b32 s36, v6, 5
	v_pk_mul_f32 v[112:113], s[36:37], v[28:29] op_sel_hi:[0,1]
	v_pk_mul_f32 v[114:115], s[36:37], v[30:31] op_sel_hi:[0,1]
	v_pk_fma_f32 v[112:113], v[118:119], v[104:105], v[112:113] op_sel_hi:[0,1,1] neg_lo:[0,0,1] neg_hi:[0,0,1]
	v_pk_fma_f32 v[114:115], v[118:119], v[106:107], v[114:115] op_sel_hi:[0,1,1] neg_lo:[0,0,1] neg_hi:[0,0,1]
	v_pk_mul_f32 v[112:113], v[108:109], v[112:113]
	v_pk_mul_f32 v[114:115], v[110:111], v[114:115]
	v_cvt_pk_bf16_f32 v128, v112, v113
	v_cvt_pk_bf16_f32 v129, v114, v115
	s_add_i32 s47, s28, s40
	s_add_i32 s47, s47, 3
	s_lshl_b32 s47, s47, 11
	v_add_u32_e32 v130, s47, v7
	global_store_dwordx2 v130, v[128:129], s[22:23]
	s_lshl_b32 s40, s34, 3
	s_add_i32 s40, s40, 4
	s_lshl_b32 s41, s40, 10
	v_add_u32_e32 v4, s41, v1
	ds_read_b128 v[8:11], v4
	ds_read_b128 v[12:15], v4 offset:1024
	ds_read_b128 v[16:19], v4 offset:2048
	ds_read_b128 v[20:23], v4 offset:3072
	ds_read_b128 v[24:27], v4 offset:4096
	ds_read_b128 v[28:31], v4 offset:5120
	ds_read_b128 v[32:35], v4 offset:6144
	s_add_i32 s41, s31, s40
	s_sub_i32 s41, s41, 2
	v_add_u32_e32 v5, s41, v0
	v_cmp_le_i32_e64 s[36:37], 0, v5
	v_cmp_gt_i32_e64 s[12:13], s30, v5
	s_and_b64 s[36:37], s[36:37], s[12:13]
	v_max_i32_e32 v5, 0, v5
	s_add_i32 s41, s30, -1
	v_min_i32_e32 v5, s41, v5
	v_add_u32_e32 v5, s29, v5
	v_lshlrev_b32_e32 v5, 2, v5
	global_load_dword v6, v5, s[18:19]
	s_waitcnt vmcnt(0)
	v_cndmask_b32_e64 v6, 0, v6, s[36:37]
	s_add_i32 s45, s31, s40
	s_waitcnt lgkmcnt(0)
	v_readlane_b32 s36, v6, 0
	v_pk_fma_f32 v[104:105], s[36:37], v[8:9], 0 op_sel_hi:[0,1,0]
	v_pk_fma_f32 v[106:107], s[36:37], v[10:11], 0 op_sel_hi:[0,1,0]
	v_readlane_b32 s12, v6, 1
	v_pk_fma_f32 v[104:105], s[12:13], v[12:13], v[104:105] op_sel_hi:[0,1,1]
	v_pk_fma_f32 v[106:107], s[12:13], v[14:15], v[106:107] op_sel_hi:[0,1,1]
	v_readlane_b32 s36, v6, 2
	v_pk_fma_f32 v[104:105], s[36:37], v[16:17], v[104:105] op_sel_hi:[0,1,1]
	v_pk_fma_f32 v[106:107], s[36:37], v[18:19], v[106:107] op_sel_hi:[0,1,1]
	v_readlane_b32 s12, v6, 3
	v_pk_fma_f32 v[104:105], s[12:13], v[20:21], v[104:105] op_sel_hi:[0,1,1]
	v_pk_fma_f32 v[106:107], s[12:13], v[22:23], v[106:107] op_sel_hi:[0,1,1]
	s_add_i32 s47, s45, 2
	s_min_u32 s47, s47, s30
	s_add_i32 s50, s45, -2
	s_max_i32 s50, s50, 0
	s_sub_i32 s47, s47, s50
	v_cvt_f32_i32_e32 v116, s47
	v_div_scale_f32 v120, s[12:13], v116, v116, 1.0
	v_rcp_f32_e32 v121, v120
	v_div_scale_f32 v122, vcc, 1.0, v116, 1.0
	s_nop 0
	v_fma_f32 v124, -v120, v121, 1.0
	v_fmac_f32_e32 v121, v124, v121
	v_mul_f32_e32 v123, v122, v121
	v_fma_f32 v124, -v120, v123, v122
	v_fmac_f32_e32 v123, v124, v121
	v_fma_f32 v120, -v120, v123, v122
	v_div_fmas_f32 v120, v120, v121, v123
	v_div_fixup_f32 v118, v120, v116, 1.0
	v_readlane_b32 s36, v6, 2
	v_pk_mul_f32 v[112:113], s[36:37], v[16:17] op_sel_hi:[0,1]
	v_pk_mul_f32 v[114:115], s[36:37], v[18:19] op_sel_hi:[0,1]
	v_pk_fma_f32 v[112:113], v[118:119], v[104:105], v[112:113] op_sel_hi:[0,1,1] neg_lo:[0,0,1] neg_hi:[0,0,1]
	v_pk_fma_f32 v[114:115], v[118:119], v[106:107], v[114:115] op_sel_hi:[0,1,1] neg_lo:[0,0,1] neg_hi:[0,0,1]
	v_pk_mul_f32 v[112:113], v[108:109], v[112:113]
	v_pk_mul_f32 v[114:115], v[110:111], v[114:115]
	v_cvt_pk_bf16_f32 v128, v112, v113
	v_cvt_pk_bf16_f32 v129, v114, v115
	s_add_i32 s47, s28, s40
	s_add_i32 s47, s47, 0
	s_lshl_b32 s47, s47, 11
	v_add_u32_e32 v130, s47, v7
	global_store_dwordx2 v130, v[128:129], s[22:23]
	v_readlane_b32 s36, v6, 0
	v_readlane_b32 s12, v6, 4
	v_pk_mul_f32 v[112:113], s[36:37], v[8:9] op_sel_hi:[0,1]
	v_pk_mul_f32 v[114:115], s[36:37], v[10:11] op_sel_hi:[0,1]
	v_pk_fma_f32 v[112:113], s[12:13], v[24:25], v[112:113] op_sel_hi:[0,1,1] neg_lo:[0,0,1] neg_hi:[0,0,1]
	v_pk_fma_f32 v[114:115], s[12:13], v[26:27], v[114:115] op_sel_hi:[0,1,1] neg_lo:[0,0,1] neg_hi:[0,0,1]
	v_pk_add_f32 v[104:105], v[104:105], v[112:113]
	v_pk_add_f32 v[106:107], v[106:107], v[114:115]
	s_add_i32 s47, s45, 3
	s_min_u32 s47, s47, s30
	s_add_i32 s50, s45, -1
	s_max_i32 s50, s50, 0
	s_sub_i32 s47, s47, s50
	v_cvt_f32_i32_e32 v116, s47
	v_div_scale_f32 v120, s[12:13], v116, v116, 1.0
	v_rcp_f32_e32 v121, v120
	v_div_scale_f32 v122, vcc, 1.0, v116, 1.0
	s_nop 0
	v_fma_f32 v124, -v120, v121, 1.0
	v_fmac_f32_e32 v121, v124, v121
	v_mul_f32_e32 v123, v122, v121
	v_fma_f32 v124, -v120, v123, v122
	v_fmac_f32_e32 v123, v124, v121
	v_fma_f32 v120, -v120, v123, v122
	v_div_fmas_f32 v120, v120, v121, v123
	v_div_fixup_f32 v118, v120, v116, 1.0
	v_readlane_b32 s36, v6, 3
	v_pk_mul_f32 v[112:113], s[36:37], v[20:21] op_sel_hi:[0,1]
	v_pk_mul_f32 v[114:115], s[36:37], v[22:23] op_sel_hi:[0,1]
	v_pk_fma_f32 v[112:113], v[118:119], v[104:105], v[112:113] op_sel_hi:[0,1,1] neg_lo:[0,0,1] neg_hi:[0,0,1]
	v_pk_fma_f32 v[114:115], v[118:119], v[106:107], v[114:115] op_sel_hi:[0,1,1] neg_lo:[0,0,1] neg_hi:[0,0,1]
	v_pk_mul_f32 v[112:113], v[108:109], v[112:113]
	v_pk_mul_f32 v[114:115], v[110:111], v[114:115]
	v_cvt_pk_bf16_f32 v128, v112, v113
	v_cvt_pk_bf16_f32 v129, v114, v115
	s_add_i32 s47, s28, s40
	s_add_i32 s47, s47, 1
	s_lshl_b32 s47, s47, 11
	v_add_u32_e32 v130, s47, v7
	global_store_dwordx2 v130, v[128:129], s[22:23]
	v_readlane_b32 s36, v6, 1
	v_readlane_b32 s12, v6, 5
	v_pk_mul_f32 v[112:113], s[36:37], v[12:13] op_sel_hi:[0,1]
	v_pk_mul_f32 v[114:115], s[36:37], v[14:15] op_sel_hi:[0,1]
	v_pk_fma_f32 v[112:113], s[12:13], v[28:29], v[112:113] op_sel_hi:[0,1,1] neg_lo:[0,0,1] neg_hi:[0,0,1]
	v_pk_fma_f32 v[114:115], s[12:13], v[30:31], v[114:115] op_sel_hi:[0,1,1] neg_lo:[0,0,1] neg_hi:[0,0,1]
	v_pk_add_f32 v[104:105], v[104:105], v[112:113]
	v_pk_add_f32 v[106:107], v[106:107], v[114:115]
	s_add_i32 s47, s45, 4
	s_min_u32 s47, s47, s30
	s_add_i32 s50, s45, 0
	s_max_i32 s50, s50, 0
	s_sub_i32 s47, s47, s50
	v_cvt_f32_i32_e32 v116, s47
	v_div_scale_f32 v120, s[12:13], v116, v116, 1.0
	v_rcp_f32_e32 v121, v120
	v_div_scale_f32 v122, vcc, 1.0, v116, 1.0
	s_nop 0
	v_fma_f32 v124, -v120, v121, 1.0
	v_fmac_f32_e32 v121, v124, v121
	v_mul_f32_e32 v123, v122, v121
	v_fma_f32 v124, -v120, v123, v122
	v_fmac_f32_e32 v123, v124, v121
	v_fma_f32 v120, -v120, v123, v122
	v_div_fmas_f32 v120, v120, v121, v123
	v_div_fixup_f32 v118, v120, v116, 1.0
	v_readlane_b32 s36, v6, 4
	v_pk_mul_f32 v[112:113], s[36:37], v[24:25] op_sel_hi:[0,1]
	v_pk_mul_f32 v[114:115], s[36:37], v[26:27] op_sel_hi:[0,1]
	v_pk_fma_f32 v[112:113], v[118:119], v[104:105], v[112:113] op_sel_hi:[0,1,1] neg_lo:[0,0,1] neg_hi:[0,0,1]
	v_pk_fma_f32 v[114:115], v[118:119], v[106:107], v[114:115] op_sel_hi:[0,1,1] neg_lo:[0,0,1] neg_hi:[0,0,1]
	v_pk_mul_f32 v[112:113], v[108:109], v[112:113]
	v_pk_mul_f32 v[114:115], v[110:111], v[114:115]
	v_cvt_pk_bf16_f32 v128, v112, v113
	v_cvt_pk_bf16_f32 v129, v114, v115
	s_add_i32 s47, s28, s40
	s_add_i32 s47, s47, 2
	s_lshl_b32 s47, s47, 11
	v_add_u32_e32 v130, s47, v7
	global_store_dwordx2 v130, v[128:129], s[22:23]
	v_readlane_b32 s36, v6, 2
	v_readlane_b32 s12, v6, 6
	v_pk_mul_f32 v[112:113], s[36:37], v[16:17] op_sel_hi:[0,1]
	v_pk_mul_f32 v[114:115], s[36:37], v[18:19] op_sel_hi:[0,1]
	v_pk_fma_f32 v[112:113], s[12:13], v[32:33], v[112:113] op_sel_hi:[0,1,1] neg_lo:[0,0,1] neg_hi:[0,0,1]
	v_pk_fma_f32 v[114:115], s[12:13], v[34:35], v[114:115] op_sel_hi:[0,1,1] neg_lo:[0,0,1] neg_hi:[0,0,1]
	v_pk_add_f32 v[104:105], v[104:105], v[112:113]
	v_pk_add_f32 v[106:107], v[106:107], v[114:115]
	s_add_i32 s47, s45, 5
	s_min_u32 s47, s47, s30
	s_add_i32 s50, s45, 1
	s_max_i32 s50, s50, 0
	s_sub_i32 s47, s47, s50
	v_cvt_f32_i32_e32 v116, s47
	v_div_scale_f32 v120, s[12:13], v116, v116, 1.0
	v_rcp_f32_e32 v121, v120
	v_div_scale_f32 v122, vcc, 1.0, v116, 1.0
	s_nop 0
	v_fma_f32 v124, -v120, v121, 1.0
	v_fmac_f32_e32 v121, v124, v121
	v_mul_f32_e32 v123, v122, v121
	v_fma_f32 v124, -v120, v123, v122
	v_fmac_f32_e32 v123, v124, v121
	v_fma_f32 v120, -v120, v123, v122
	v_div_fmas_f32 v120, v120, v121, v123
	v_div_fixup_f32 v118, v120, v116, 1.0
	v_readlane_b32 s36, v6, 5
	v_pk_mul_f32 v[112:113], s[36:37], v[28:29] op_sel_hi:[0,1]
	v_pk_mul_f32 v[114:115], s[36:37], v[30:31] op_sel_hi:[0,1]
	v_pk_fma_f32 v[112:113], v[118:119], v[104:105], v[112:113] op_sel_hi:[0,1,1] neg_lo:[0,0,1] neg_hi:[0,0,1]
	v_pk_fma_f32 v[114:115], v[118:119], v[106:107], v[114:115] op_sel_hi:[0,1,1] neg_lo:[0,0,1] neg_hi:[0,0,1]
	v_pk_mul_f32 v[112:113], v[108:109], v[112:113]
	v_pk_mul_f32 v[114:115], v[110:111], v[114:115]
	v_cvt_pk_bf16_f32 v128, v112, v113
	v_cvt_pk_bf16_f32 v129, v114, v115
	s_add_i32 s47, s28, s40
	s_add_i32 s47, s47, 3
	s_lshl_b32 s47, s47, 11
	v_add_u32_e32 v130, s47, v7
	global_store_dwordx2 v130, v[128:129], s[22:23]
	s_branch .Lpz_next
.Lpz_c0:
	s_lshl_b32 s40, s34, 3
	s_lshl_b32 s41, s40, 10
	v_add_u32_e32 v4, s41, v1
	ds_read_b128 v[8:11], v4
	ds_read_b128 v[12:15], v4 offset:1024
	ds_read_b128 v[16:19], v4 offset:2048
	ds_read_b128 v[20:23], v4 offset:3072
	ds_read_b128 v[24:27], v4 offset:4096
	s_add_i32 s41, s31, s40
	s_sub_i32 s41, s41, 1
	v_add_u32_e32 v5, s41, v0
	v_cmp_le_i32_e64 s[36:37], 0, v5
	v_cmp_gt_i32_e64 s[12:13], s30, v5
	s_and_b64 s[36:37], s[36:37], s[12:13]
	v_max_i32_e32 v5, 0, v5
	s_add_i32 s41, s30, -1
	v_min_i32_e32 v5, s41, v5
	v_add_u32_e32 v5, s29, v5
	v_lshlrev_b32_e32 v5, 2, v5
	global_load_dword v6, v5, s[18:19]
	s_waitcnt vmcnt(0)
	v_cndmask_b32_e64 v6, 0, v6, s[36:37]
	s_add_i32 s45, s31, s40
	s_waitcnt lgkmcnt(0)
	v_readlane_b32 s36, v6, 0
	v_pk_fma_f32 v[104:105], s[36:37], v[8:9], 0 op_sel_hi:[0,1,0]
	v_pk_fma_f32 v[106:107], s[36:37], v[10:11], 0 op_sel_hi:[0,1,0]
	v_readlane_b32 s12, v6, 1
	v_pk_fma_f32 v[104:105], s[12:13], v[12:13], v[104:105] op_sel_hi:[0,1,1]
	v_pk_fma_f32 v[106:107], s[12:13], v[14:15], v[106:107] op_sel_hi:[0,1,1]
	s_add_i32 s47, s45, 1
	s_min_u32 s47, s47, s30
	s_add_i32 s50, s45, -1
	s_max_i32 s50, s50, 0
	s_sub_i32 s47, s47, s50
	v_cvt_f32_i32_e32 v116, s47
	v_div_scale_f32 v120, s[12:13], v116, v116, 1.0
	v_rcp_f32_e32 v121, v120
	v_div_scale_f32 v122, vcc, 1.0, v116, 1.0
	s_nop 0
	v_fma_f32 v124, -v120, v121, 1.0
	v_fmac_f32_e32 v121, v124, v121
	v_mul_f32_e32 v123, v122, v121
	v_fma_f32 v124, -v120, v123, v122
	v_fmac_f32_e32 v123, v124, v121
	v_fma_f32 v120, -v120, v123, v122
	v_div_fmas_f32 v120, v120, v121, v123
	v_div_fixup_f32 v118, v120, v116, 1.0
	v_readlane_b32 s36, v6, 1
	v_pk_mul_f32 v[112:113], s[36:37], v[12:13] op_sel_hi:[0,1]
	v_pk_mul_f32 v[114:115], s[36:37], v[14:15] op_sel_hi:[0,1]
	v_pk_fma_f32 v[112:113], v[118:119], v[104:105], v[112:113] op_sel_hi:[0,1,1] neg_lo:[0,0,1] neg_hi:[0,0,1]
	v_pk_fma_f32 v[114:115], v[118:119], v[106:107], v[114:115] op_sel_hi:[0,1,1] neg_lo:[0,0,1] neg_hi:[0,0,1]
	v_pk_mul_f32 v[112:113], v[108:109], v[112:113]
	v_pk_mul_f32 v[114:115], v[110:111], v[114:115]
	v_cvt_pk_bf16_f32 v128, v112, v113
	v_cvt_pk_bf16_f32 v129, v114, v115
	s_add_i32 s47, s28, s40
	s_add_i32 s47, s47, 0
	s_lshl_b32 s47, s47, 11
	v_add_u32_e32 v130, s47, v7
	global_store_dwordx2 v130, v[128:129], s[22:23]
	v_readlane_b32 s36, v6, 0
	v_readlane_b32 s12, v6, 2
	v_pk_mul_f32 v[112:113], s[36:37], v[8:9] op_sel_hi:[0,1]
	v_pk_mul_f32 v[114:115], s[36:37], v[10:11] op_sel_hi:[0,1]
	v_pk_fma_f32 v[112:113], s[12:13], v[16:17], v[112:113] op_sel_hi:[0,1,1] neg_lo:[0,0,1] neg_hi:[0,0,1]
	v_pk_fma_f32 v[114:115], s[12:13], v[18:19], v[114:115] op_sel_hi:[0,1,1] neg_lo:[0,0,1] neg_hi:[0,0,1]
	v_pk_add_f32 v[104:105], v[104:105], v[112:113]
	v_pk_add_f32 v[106:107], v[106:107], v[114:115]
	s_add_i32 s47, s45, 2
	s_min_u32 s47, s47, s30
	s_add_i32 s50, s45, 0
	s_max_i32 s50, s50, 0
	s_sub_i32 s47, s47, s50
	v_cvt_f32_i32_e32 v116, s47
	v_div_scale_f32 v120, s[12:13], v116, v116, 1.0
	v_rcp_f32_e32 v121, v120
	v_div_scale_f32 v122, vcc, 1.0, v116, 1.0
	s_nop 0
	v_fma_f32 v124, -v120, v121, 1.0
	v_fmac_f32_e32 v121, v124, v121
	v_mul_f32_e32 v123, v122, v121
	v_fma_f32 v124, -v120, v123, v122
	v_fmac_f32_e32 v123, v124, v121
	v_fma_f32 v120, -v120, v123, v122
	v_div_fmas_f32 v120, v120, v121, v123
	v_div_fixup_f32 v118, v120, v116, 1.0
	v_readlane_b32 s36, v6, 2
	v_pk_mul_f32 v[112:113], s[36:37], v[16:17] op_sel_hi:[0,1]
	v_pk_mul_f32 v[114:115], s[36:37], v[18:19] op_sel_hi:[0,1]
	v_pk_fma_f32 v[112:113], v[118:119], v[104:105], v[112:113] op_sel_hi:[0,1,1] neg_lo:[0,0,1] neg_hi:[0,0,1]
	v_pk_fma_f32 v[114:115], v[118:119], v[106:107], v[114:115] op_sel_hi:[0,1,1] neg_lo:[0,0,1] neg_hi:[0,0,1]
	v_pk_mul_f32 v[112:113], v[108:109], v[112:113]
	v_pk_mul_f32 v[114:115], v[110:111], v[114:115]
	v_cvt_pk_bf16_f32 v128, v112, v113
	v_cvt_pk_bf16_f32 v129, v114, v115
	s_add_i32 s47, s28, s40
	s_add_i32 s47, s47, 1
	s_lshl_b32 s47, s47, 11
	v_add_u32_e32 v130, s47, v7
	global_store_dwordx2 v130, v[128:129], s[22:23]
	v_readlane_b32 s36, v6, 1
	v_readlane_b32 s12, v6, 3
	v_pk_mul_f32 v[112:113], s[36:37], v[12:13] op_sel_hi:[0,1]
	v_pk_mul_f32 v[114:115], s[36:37], v[14:15] op_sel_hi:[0,1]
	v_pk_fma_f32 v[112:113], s[12:13], v[20:21], v[112:113] op_sel_hi:[0,1,1] neg_lo:[0,0,1] neg_hi:[0,0,1]
	v_pk_fma_f32 v[114:115], s[12:13], v[22:23], v[114:115] op_sel_hi:[0,1,1] neg_lo:[0,0,1] neg_hi:[0,0,1]
	v_pk_add_f32 v[104:105], v[104:105], v[112:113]
	v_pk_add_f32 v[106:107], v[106:107], v[114:115]
	s_add_i32 s47, s45, 3
	s_min_u32 s47, s47, s30
	s_add_i32 s50, s45, 1
	s_max_i32 s50, s50, 0
	s_sub_i32 s47, s47, s50
	v_cvt_f32_i32_e32 v116, s47
	v_div_scale_f32 v120, s[12:13], v116, v116, 1.0
	v_rcp_f32_e32 v121, v120
	v_div_scale_f32 v122, vcc, 1.0, v116, 1.0
	s_nop 0
	v_fma_f32 v124, -v120, v121, 1.0
	v_fmac_f32_e32 v121, v124, v121
	v_mul_f32_e32 v123, v122, v121
	v_fma_f32 v124, -v120, v123, v122
	v_fmac_f32_e32 v123, v124, v121
	v_fma_f32 v120, -v120, v123, v122
	v_div_fmas_f32 v120, v120, v121, v123
	v_div_fixup_f32 v118, v120, v116, 1.0
	v_readlane_b32 s36, v6, 3
	v_pk_mul_f32 v[112:113], s[36:37], v[20:21] op_sel_hi:[0,1]
	v_pk_mul_f32 v[114:115], s[36:37], v[22:23] op_sel_hi:[0,1]
	v_pk_fma_f32 v[112:113], v[118:119], v[104:105], v[112:113] op_sel_hi:[0,1,1] neg_lo:[0,0,1] neg_hi:[0,0,1]
	v_pk_fma_f32 v[114:115], v[118:119], v[106:107], v[114:115] op_sel_hi:[0,1,1] neg_lo:[0,0,1] neg_hi:[0,0,1]
	v_pk_mul_f32 v[112:113], v[108:109], v[112:113]
	v_pk_mul_f32 v[114:115], v[110:111], v[114:115]
	v_cvt_pk_bf16_f32 v128, v112, v113
	v_cvt_pk_bf16_f32 v129, v114, v115
	s_add_i32 s47, s28, s40
	s_add_i32 s47, s47, 2
	s_lshl_b32 s47, s47, 11
	v_add_u32_e32 v130, s47, v7
	global_store_dwordx2 v130, v[128:129], s[22:23]
	v_readlane_b32 s36, v6, 2
	v_readlane_b32 s12, v6, 4
	v_pk_mul_f32 v[112:113], s[36:37], v[16:17] op_sel_hi:[0,1]
	v_pk_mul_f32 v[114:115], s[36:37], v[18:19] op_sel_hi:[0,1]
	v_pk_fma_f32 v[112:113], s[12:13], v[24:25], v[112:113] op_sel_hi:[0,1,1] neg_lo:[0,0,1] neg_hi:[0,0,1]
	v_pk_fma_f32 v[114:115], s[12:13], v[26:27], v[114:115] op_sel_hi:[0,1,1] neg_lo:[0,0,1] neg_hi:[0,0,1]
	v_pk_add_f32 v[104:105], v[104:105], v[112:113]
	v_pk_add_f32 v[106:107], v[106:107], v[114:115]
	s_add_i32 s47, s45, 4
	s_min_u32 s47, s47, s30
	s_add_i32 s50, s45, 2
	s_max_i32 s50, s50, 0
	s_sub_i32 s47, s47, s50
	v_cvt_f32_i32_e32 v116, s47
	v_div_scale_f32 v120, s[12:13], v116, v116, 1.0
	v_rcp_f32_e32 v121, v120
	v_div_scale_f32 v122, vcc, 1.0, v116, 1.0
	s_nop 0
	v_fma_f32 v124, -v120, v121, 1.0
	v_fmac_f32_e32 v121, v124, v121
	v_mul_f32_e32 v123, v122, v121
	v_fma_f32 v124, -v120, v123, v122
	v_fmac_f32_e32 v123, v124, v121
	v_fma_f32 v120, -v120, v123, v122
	v_div_fmas_f32 v120, v120, v121, v123
	v_div_fixup_f32 v118, v120, v116, 1.0
	v_readlane_b32 s36, v6, 4
	v_pk_mul_f32 v[112:113], s[36:37], v[24:25] op_sel_hi:[0,1]
	v_pk_mul_f32 v[114:115], s[36:37], v[26:27] op_sel_hi:[0,1]
	v_pk_fma_f32 v[112:113], v[118:119], v[104:105], v[112:113] op_sel_hi:[0,1,1] neg_lo:[0,0,1] neg_hi:[0,0,1]
	v_pk_fma_f32 v[114:115], v[118:119], v[106:107], v[114:115] op_sel_hi:[0,1,1] neg_lo:[0,0,1] neg_hi:[0,0,1]
	v_pk_mul_f32 v[112:113], v[108:109], v[112:113]
	v_pk_mul_f32 v[114:115], v[110:111], v[114:115]
	v_cvt_pk_bf16_f32 v128, v112, v113
	v_cvt_pk_bf16_f32 v129, v114, v115
	s_add_i32 s47, s28, s40
	s_add_i32 s47, s47, 3
	s_lshl_b32 s47, s47, 11
	v_add_u32_e32 v130, s47, v7
	global_store_dwordx2 v130, v[128:129], s[22:23]
	s_lshl_b32 s40, s34, 3
	s_add_i32 s40, s40, 4
	s_lshl_b32 s41, s40, 10
	v_add_u32_e32 v4, s41, v1
	ds_read_b128 v[8:11], v4
	ds_read_b128 v[12:15], v4 offset:1024
	ds_read_b128 v[16:19], v4 offset:2048
	ds_read_b128 v[20:23], v4 offset:3072
	ds_read_b128 v[24:27], v4 offset:4096
	s_add_i32 s41, s31, s40
	s_sub_i32 s41, s41, 1
	v_add_u32_e32 v5, s41, v0
	v_cmp_le_i32_e64 s[36:37], 0, v5
	v_cmp_gt_i32_e64 s[12:13], s30, v5
	s_and_b64 s[36:37], s[36:37], s[12:13]
	v_max_i32_e32 v5, 0, v5
	s_add_i32 s41, s30, -1
	v_min_i32_e32 v5, s41, v5
	v_add_u32_e32 v5, s29, v5
	v_lshlrev_b32_e32 v5, 2, v5
	global_load_dword v6, v5, s[18:19]
	s_waitcnt vmcnt(0)
	v_cndmask_b32_e64 v6, 0, v6, s[36:37]
	s_add_i32 s45, s31, s40
	s_waitcnt lgkmcnt(0)
	v_readlane_b32 s36, v6, 0
	v_pk_fma_f32 v[104:105], s[36:37], v[8:9], 0 op_sel_hi:[0,1,0]
	v_pk_fma_f32 v[106:107], s[36:37], v[10:11], 0 op_sel_hi:[0,1,0]
	v_readlane_b32 s12, v6, 1
	v_pk_fma_f32 v[104:105], s[12:13], v[12:13], v[104:105] op_sel_hi:[0,1,1]
	v_pk_fma_f32 v[106:107], s[12:13], v[14:15], v[106:107] op_sel_hi:[0,1,1]
	s_add_i32 s47, s45, 1
	s_min_u32 s47, s47, s30
	s_add_i32 s50, s45, -1
	s_max_i32 s50, s50, 0
	s_sub_i32 s47, s47, s50
	v_cvt_f32_i32_e32 v116, s47
	v_div_scale_f32 v120, s[12:13], v116, v116, 1.0
	v_rcp_f32_e32 v121, v120
	v_div_scale_f32 v122, vcc, 1.0, v116, 1.0
	s_nop 0
	v_fma_f32 v124, -v120, v121, 1.0
	v_fmac_f32_e32 v121, v124, v121
	v_mul_f32_e32 v123, v122, v121
	v_fma_f32 v124, -v120, v123, v122
	v_fmac_f32_e32 v123, v124, v121
	v_fma_f32 v120, -v120, v123, v122
	v_div_fmas_f32 v120, v120, v121, v123
	v_div_fixup_f32 v118, v120, v116, 1.0
	v_readlane_b32 s36, v6, 1
	v_pk_mul_f32 v[112:113], s[36:37], v[12:13] op_sel_hi:[0,1]
	v_pk_mul_f32 v[114:115], s[36:37], v[14:15] op_sel_hi:[0,1]
	v_pk_fma_f32 v[112:113], v[118:119], v[104:105], v[112:113] op_sel_hi:[0,1,1] neg_lo:[0,0,1] neg_hi:[0,0,1]
	v_pk_fma_f32 v[114:115], v[118:119], v[106:107], v[114:115] op_sel_hi:[0,1,1] neg_lo:[0,0,1] neg_hi:[0,0,1]
	v_pk_mul_f32 v[112:113], v[108:109], v[112:113]
	v_pk_mul_f32 v[114:115], v[110:111], v[114:115]
	v_cvt_pk_bf16_f32 v128, v112, v113
	v_cvt_pk_bf16_f32 v129, v114, v115
	s_add_i32 s47, s28, s40
	s_add_i32 s47, s47, 0
	s_lshl_b32 s47, s47, 11
	v_add_u32_e32 v130, s47, v7
	global_store_dwordx2 v130, v[128:129], s[22:23]
	v_readlane_b32 s36, v6, 0
	v_readlane_b32 s12, v6, 2
	v_pk_mul_f32 v[112:113], s[36:37], v[8:9] op_sel_hi:[0,1]
	v_pk_mul_f32 v[114:115], s[36:37], v[10:11] op_sel_hi:[0,1]
	v_pk_fma_f32 v[112:113], s[12:13], v[16:17], v[112:113] op_sel_hi:[0,1,1] neg_lo:[0,0,1] neg_hi:[0,0,1]
	v_pk_fma_f32 v[114:115], s[12:13], v[18:19], v[114:115] op_sel_hi:[0,1,1] neg_lo:[0,0,1] neg_hi:[0,0,1]
	v_pk_add_f32 v[104:105], v[104:105], v[112:113]
	v_pk_add_f32 v[106:107], v[106:107], v[114:115]
	s_add_i32 s47, s45, 2
	s_min_u32 s47, s47, s30
	s_add_i32 s50, s45, 0
	s_max_i32 s50, s50, 0
	s_sub_i32 s47, s47, s50
	v_cvt_f32_i32_e32 v116, s47
	v_div_scale_f32 v120, s[12:13], v116, v116, 1.0
	v_rcp_f32_e32 v121, v120
	v_div_scale_f32 v122, vcc, 1.0, v116, 1.0
	s_nop 0
	v_fma_f32 v124, -v120, v121, 1.0
	v_fmac_f32_e32 v121, v124, v121
	v_mul_f32_e32 v123, v122, v121
	v_fma_f32 v124, -v120, v123, v122
	v_fmac_f32_e32 v123, v124, v121
	v_fma_f32 v120, -v120, v123, v122
	v_div_fmas_f32 v120, v120, v121, v123
	v_div_fixup_f32 v118, v120, v116, 1.0
	v_readlane_b32 s36, v6, 2
	v_pk_mul_f32 v[112:113], s[36:37], v[16:17] op_sel_hi:[0,1]
	v_pk_mul_f32 v[114:115], s[36:37], v[18:19] op_sel_hi:[0,1]
	v_pk_fma_f32 v[112:113], v[118:119], v[104:105], v[112:113] op_sel_hi:[0,1,1] neg_lo:[0,0,1] neg_hi:[0,0,1]
	v_pk_fma_f32 v[114:115], v[118:119], v[106:107], v[114:115] op_sel_hi:[0,1,1] neg_lo:[0,0,1] neg_hi:[0,0,1]
	v_pk_mul_f32 v[112:113], v[108:109], v[112:113]
	v_pk_mul_f32 v[114:115], v[110:111], v[114:115]
	v_cvt_pk_bf16_f32 v128, v112, v113
	v_cvt_pk_bf16_f32 v129, v114, v115
	s_add_i32 s47, s28, s40
	s_add_i32 s47, s47, 1
	s_lshl_b32 s47, s47, 11
	v_add_u32_e32 v130, s47, v7
	global_store_dwordx2 v130, v[128:129], s[22:23]
	v_readlane_b32 s36, v6, 1
	v_readlane_b32 s12, v6, 3
	v_pk_mul_f32 v[112:113], s[36:37], v[12:13] op_sel_hi:[0,1]
	v_pk_mul_f32 v[114:115], s[36:37], v[14:15] op_sel_hi:[0,1]
	v_pk_fma_f32 v[112:113], s[12:13], v[20:21], v[112:113] op_sel_hi:[0,1,1] neg_lo:[0,0,1] neg_hi:[0,0,1]
	v_pk_fma_f32 v[114:115], s[12:13], v[22:23], v[114:115] op_sel_hi:[0,1,1] neg_lo:[0,0,1] neg_hi:[0,0,1]
	v_pk_add_f32 v[104:105], v[104:105], v[112:113]
	v_pk_add_f32 v[106:107], v[106:107], v[114:115]
	s_add_i32 s47, s45, 3
	s_min_u32 s47, s47, s30
	s_add_i32 s50, s45, 1
	s_max_i32 s50, s50, 0
	s_sub_i32 s47, s47, s50
	v_cvt_f32_i32_e32 v116, s47
	v_div_scale_f32 v120, s[12:13], v116, v116, 1.0
	v_rcp_f32_e32 v121, v120
	v_div_scale_f32 v122, vcc, 1.0, v116, 1.0
	s_nop 0
	v_fma_f32 v124, -v120, v121, 1.0
	v_fmac_f32_e32 v121, v124, v121
	v_mul_f32_e32 v123, v122, v121
	v_fma_f32 v124, -v120, v123, v122
	v_fmac_f32_e32 v123, v124, v121
	v_fma_f32 v120, -v120, v123, v122
	v_div_fmas_f32 v120, v120, v121, v123
	v_div_fixup_f32 v118, v120, v116, 1.0
	v_readlane_b32 s36, v6, 3
	v_pk_mul_f32 v[112:113], s[36:37], v[20:21] op_sel_hi:[0,1]
	v_pk_mul_f32 v[114:115], s[36:37], v[22:23] op_sel_hi:[0,1]
	v_pk_fma_f32 v[112:113], v[118:119], v[104:105], v[112:113] op_sel_hi:[0,1,1] neg_lo:[0,0,1] neg_hi:[0,0,1]
	v_pk_fma_f32 v[114:115], v[118:119], v[106:107], v[114:115] op_sel_hi:[0,1,1] neg_lo:[0,0,1] neg_hi:[0,0,1]
	v_pk_mul_f32 v[112:113], v[108:109], v[112:113]
	v_pk_mul_f32 v[114:115], v[110:111], v[114:115]
	v_cvt_pk_bf16_f32 v128, v112, v113
	v_cvt_pk_bf16_f32 v129, v114, v115
	s_add_i32 s47, s28, s40
	s_add_i32 s47, s47, 2
	s_lshl_b32 s47, s47, 11
	v_add_u32_e32 v130, s47, v7
	global_store_dwordx2 v130, v[128:129], s[22:23]
	v_readlane_b32 s36, v6, 2
	v_readlane_b32 s12, v6, 4
	v_pk_mul_f32 v[112:113], s[36:37], v[16:17] op_sel_hi:[0,1]
	v_pk_mul_f32 v[114:115], s[36:37], v[18:19] op_sel_hi:[0,1]
	v_pk_fma_f32 v[112:113], s[12:13], v[24:25], v[112:113] op_sel_hi:[0,1,1] neg_lo:[0,0,1] neg_hi:[0,0,1]
	v_pk_fma_f32 v[114:115], s[12:13], v[26:27], v[114:115] op_sel_hi:[0,1,1] neg_lo:[0,0,1] neg_hi:[0,0,1]
	v_pk_add_f32 v[104:105], v[104:105], v[112:113]
	v_pk_add_f32 v[106:107], v[106:107], v[114:115]
	s_add_i32 s47, s45, 4
	s_min_u32 s47, s47, s30
	s_add_i32 s50, s45, 2
	s_max_i32 s50, s50, 0
	s_sub_i32 s47, s47, s50
	v_cvt_f32_i32_e32 v116, s47
	v_div_scale_f32 v120, s[12:13], v116, v116, 1.0
	v_rcp_f32_e32 v121, v120
	v_div_scale_f32 v122, vcc, 1.0, v116, 1.0
	s_nop 0
	v_fma_f32 v124, -v120, v121, 1.0
	v_fmac_f32_e32 v121, v124, v121
	v_mul_f32_e32 v123, v122, v121
	v_fma_f32 v124, -v120, v123, v122
	v_fmac_f32_e32 v123, v124, v121
	v_fma_f32 v120, -v120, v123, v122
	v_div_fmas_f32 v120, v120, v121, v123
	v_div_fixup_f32 v118, v120, v116, 1.0
	v_readlane_b32 s36, v6, 4
	v_pk_mul_f32 v[112:113], s[36:37], v[24:25] op_sel_hi:[0,1]
	v_pk_mul_f32 v[114:115], s[36:37], v[26:27] op_sel_hi:[0,1]
	v_pk_fma_f32 v[112:113], v[118:119], v[104:105], v[112:113] op_sel_hi:[0,1,1] neg_lo:[0,0,1] neg_hi:[0,0,1]
	v_pk_fma_f32 v[114:115], v[118:119], v[106:107], v[114:115] op_sel_hi:[0,1,1] neg_lo:[0,0,1] neg_hi:[0,0,1]
	v_pk_mul_f32 v[112:113], v[108:109], v[112:113]
	v_pk_mul_f32 v[114:115], v[110:111], v[114:115]
	v_cvt_pk_bf16_f32 v128, v112, v113
	v_cvt_pk_bf16_f32 v129, v114, v115
	s_add_i32 s47, s28, s40
	s_add_i32 s47, s47, 3
	s_lshl_b32 s47, s47, 11
	v_add_u32_e32 v130, s47, v7
	global_store_dwordx2 v130, v[128:129], s[22:23]
.Lpz_next:
	s_barrier
	s_add_i32 s24, s24, 0x100
	s_cmp_lt_u32 s24, 0x300
	s_cbranch_scc1 .Lpz_tile
	s_mov_b64 exec, s[14:15]
